# u12 plus: first 32 outputs per lane of the out-projection epilogue read the residual from registers preloaded up front in chain order with exact counted vmcnt waits instead of one load+vmcnt(0) per el
# speedup vs baseline: 1.0213x; 1.0130x over previous
; DI int crow(int i, int h) { return (i & 3) + 8 * (i >> 2) + 4 * h; }
; DI const float* xrow(CP p, const Ptrs& w, int l, int tok) {
;   int b = tok / TPB, i = tok - b * TPB;
;   if (l == 0) return i < CTXL ? p.in[2] + (size_t)(b * CTXL + i) * DM : p.in[0] + (size_t)(b * 8192 + i - CTXL) * DM;
;   return i < CTXL ? w.xc1 + (size_t)(b * CTXL + i) * DM : p.out + (size_t)(b * 8192 + i - CTXL) * DM;
; DI void phase_out(CP p, const Ptrs& w, int l, bf16_t* sA, bf16_t* sB) {
;     ...
;         int col = n0 + wn * 64 + ni * 32 + r;
;         float gt = gate[col];
; #pragma unroll
;         for (int i = 0; i < 16; ++i) {
;           int ii = ib + wm * 64 + mi * 32 + crow(i, h);
;           const float* src = xrow(p, w, l, b * TPB + ii);
;           float* dstp = isctx ? w.xc1 + (size_t)(b * CTXL + ii) * DM : p.out + (size_t)(b * 8192 + ii - CTXL) * DM;
;           dstp[col] = src[col] + gt * acc[mi][ni][i];
.LBB0_967:
	s_lshl_b32 s10, s39, 13
	s_addk_i32 s10, 0xff00
	s_lshl_b32 s11, s39, 8
	v_ashrrev_i32_e32 v67, 31, v66
	s_and_b64 s[4:5], s[4:5], exec
	v_lshlrev_b64 v[66:67], 13, v[66:67]
	s_cselect_b32 s39, s11, s10
	v_lshl_add_u64 v[70:71], v[70:71], 0, v[66:67]
	v_add_u32_e32 v66, s39, v72
	v_ashrrev_i32_e32 v67, 31, v66
	s_cselect_b32 s5, s13, s77
	s_cselect_b32 s4, s12, s76
	v_lshlrev_b64 v[66:67], 13, v[66:67]
	v_lshl_add_u64 v[72:73], s[4:5], 0, v[66:67]
	v_lshlrev_b64 v[66:67], 2, v[64:65]
	v_lshl_add_u64 v[70:71], v[70:71], 0, v[66:67]
	s_nop 0
	v_readfirstlane_b32 s100, v70
	v_readfirstlane_b32 s101, v71
	v_mbcnt_lo_u32_b32 v168, -1, 0
	v_mbcnt_hi_u32_b32 v168, -1, v168
	v_lshlrev_b32_e32 v168, 13, v168
	s_nop 2
	global_load_dword v169, v168, s[100:101]
	global_load_dword v169, v168, s[100:101] offset:128
	v_subrev_u32_e32 v170, s100, v70
	global_load_dword v194, v170, s[100:101]
	v_add_u32_e32 v171, 0x2000, v170
	global_load_dword v195, v171, s[100:101]
	v_add_u32_e32 v171, 0x4000, v170
	global_load_dword v196, v171, s[100:101]
	v_add_u32_e32 v171, 0x6000, v170
	global_load_dword v197, v171, s[100:101]
	v_add_u32_e32 v171, 0x10000, v170
	global_load_dword v198, v171, s[100:101]
	v_add_u32_e32 v171, 0x12000, v170
	global_load_dword v199, v171, s[100:101]
	v_add_u32_e32 v171, 0x14000, v170
	global_load_dword v200, v171, s[100:101]
	v_add_u32_e32 v171, 0x16000, v170
	global_load_dword v201, v171, s[100:101]
	v_add_u32_e32 v171, 0x20000, v170
	global_load_dword v202, v171, s[100:101]
	v_add_u32_e32 v171, 0x22000, v170
	global_load_dword v203, v171, s[100:101]
	v_add_u32_e32 v171, 0x24000, v170
	global_load_dword v204, v171, s[100:101]
	v_add_u32_e32 v171, 0x26000, v170
	global_load_dword v205, v171, s[100:101]
	v_add_u32_e32 v171, 0x30000, v170
	global_load_dword v206, v171, s[100:101]
	v_add_u32_e32 v171, 0x32000, v170
	global_load_dword v207, v171, s[100:101]
	v_add_u32_e32 v171, 0x34000, v170
	global_load_dword v208, v171, s[100:101]
	v_add_u32_e32 v171, 0x36000, v170
	global_load_dword v209, v171, s[100:101]
	v_add_u32_e32 v171, 0x40000, v170
	global_load_dword v210, v171, s[100:101]
	v_add_u32_e32 v171, 0x42000, v170
	global_load_dword v211, v171, s[100:101]
	v_add_u32_e32 v171, 0x44000, v170
	global_load_dword v212, v171, s[100:101]
	v_add_u32_e32 v171, 0x46000, v170
	global_load_dword v213, v171, s[100:101]
	v_add_u32_e32 v171, 0x50000, v170
	global_load_dword v172, v171, s[100:101]
	v_add_u32_e32 v171, 0x52000, v170
	global_load_dword v173, v171, s[100:101]
	v_add_u32_e32 v171, 0x54000, v170
	global_load_dword v174, v171, s[100:101]
	v_add_u32_e32 v171, 0x56000, v170
	global_load_dword v175, v171, s[100:101]
	v_add_u32_e32 v171, 0x60000, v170
	global_load_dword v176, v171, s[100:101]
	v_add_u32_e32 v171, 0x62000, v170
	global_load_dword v177, v171, s[100:101]
	v_add_u32_e32 v171, 0x64000, v170
	global_load_dword v178, v171, s[100:101]
	v_add_u32_e32 v171, 0x66000, v170
	global_load_dword v179, v171, s[100:101]
	v_add_u32_e32 v171, 0x70000, v170
	global_load_dword v132, v171, s[100:101]
	v_add_u32_e32 v171, 0x72000, v170
	global_load_dword v133, v171, s[100:101]
	v_add_u32_e32 v171, 0x74000, v170
	global_load_dword v134, v171, s[100:101]
	v_add_u32_e32 v171, 0x76000, v170
	global_load_dword v135, v171, s[100:101]
	v_lshl_add_u64 v[70:71], v[72:73], 0, v[66:67]
	v_readlane_b32 s46, v254, 54
	v_readlane_b32 s47, v254, 55
	s_mov_b64 s[10:11], -1
	s_andn2_b64 vcc, exec, s[46:47]
	s_waitcnt vmcnt(31)
	v_fma_f32 v74, v48, v90, v194
	v_or_b32_e32 v48, v92, v167
	v_add_u32_e32 v72, s38, v48
	v_mul_hi_i32 v73, v72, s0
	global_store_dword v[70:71], v74, off
	v_lshrrev_b32_e32 v74, 31, v73
	v_ashrrev_i32_e32 v73, 11, v73
	v_add_u32_e32 v95, v73, v74
	v_mad_i32_i24 v96, v95, s1, v72
	v_cndmask_b32_e64 v72, 0, 1, s[46:47]
	v_cmp_lt_i32_e64 s[44:45], s37, v96
	v_cmp_ne_u32_e64 s[40:41], 1, v72
	s_cbranch_vccnz .LBB0_973
	s_and_saveexec_b64 s[10:11], s[44:45]
	s_xor_b64 s[10:11], exec, s[10:11]
	v_lshlrev_b32_e32 v72, 13, v95
	s_movk_i32 s46, 0xff00
	v_add3_u32 v72, v72, v96, s46
	s_or_saveexec_b64 s[10:11], s[10:11]
	v_mov_b64_e32 v[74:75], s[76:77]
	s_xor_b64 exec, exec, s[10:11]
	v_lshl_add_u32 v72, v95, 8, v96
	v_mov_b64_e32 v[74:75], s[12:13]
	s_or_b64 exec, exec, s[10:11]
	s_mov_b64 s[10:11], 0

; DI int crow(int i, int h) { return (i & 3) + 8 * (i >> 2) + 4 * h; }
; DI const float* xrow(CP p, const Ptrs& w, int l, int tok) {
;   int b = tok / TPB, i = tok - b * TPB;
;   if (l == 0) return i < CTXL ? p.in[2] + (size_t)(b * CTXL + i) * DM : p.in[0] + (size_t)(b * 8192 + i - CTXL) * DM;
;   return i < CTXL ? w.xc1 + (size_t)(b * CTXL + i) * DM : p.out + (size_t)(b * 8192 + i - CTXL) * DM;
; DI void phase_out(CP p, const Ptrs& w, int l, bf16_t* sA, bf16_t* sB) {
;     ...
;         int col = n0 + wn * 64 + ni * 32 + r;
;         float gt = gate[col];
; #pragma unroll
;         for (int i = 0; i < 16; ++i) {
;           int ii = ib + wm * 64 + mi * 32 + crow(i, h);
;           const float* src = xrow(p, w, l, b * TPB + ii);
;           float* dstp = isctx ? w.xc1 + (size_t)(b * CTXL + ii) * DM : p.out + (size_t)(b * 8192 + ii - CTXL) * DM;
;           dstp[col] = src[col] + gt * acc[mi][ni][i];
.LBB0_979:
	v_ashrrev_i32_e32 v73, 31, v72
	v_lshlrev_b64 v[72:73], 13, v[72:73]
	v_lshl_add_u64 v[72:73], v[74:75], 0, v[72:73]
	v_lshl_add_u64 v[72:73], v[72:73], 0, v[66:67]
	v_add_u32_e32 v74, s39, v48
	v_ashrrev_i32_e32 v75, 31, v74
	v_lshlrev_b64 v[74:75], 13, v[74:75]
	v_lshl_add_u64 v[74:75], s[4:5], 0, v[74:75]
	v_lshl_add_u64 v[72:73], v[74:75], 0, v[66:67]
	v_or_b32_e32 v76, v92, v180
	s_mov_b64 s[10:11], -1
	s_and_b64 vcc, exec, s[40:41]
	s_waitcnt vmcnt(31)
	v_fma_f32 v48, v49, v90, v195
	global_store_dword v[72:73], v48, off
	v_add_u32_e32 v48, s38, v76
	v_mul_hi_i32 v49, v48, s0
	v_lshrrev_b32_e32 v74, 31, v49
	v_ashrrev_i32_e32 v49, 11, v49
	v_add_u32_e32 v97, v49, v74
	v_mad_i32_i24 v98, v97, s1, v48
	v_cmp_lt_i32_e64 s[46:47], s37, v98
	s_cbranch_vccnz .LBB0_985
	s_and_saveexec_b64 s[10:11], s[46:47]
	s_xor_b64 s[10:11], exec, s[10:11]
	v_lshlrev_b32_e32 v48, 13, v97
	s_movk_i32 s48, 0xff00
	v_add3_u32 v48, v48, v98, s48
	s_or_saveexec_b64 s[10:11], s[10:11]
	v_mov_b64_e32 v[74:75], s[76:77]
	s_xor_b64 exec, exec, s[10:11]
	v_lshl_add_u32 v48, v97, 8, v98
	v_mov_b64_e32 v[74:75], s[12:13]
	s_or_b64 exec, exec, s[10:11]
	s_mov_b64 s[10:11], 0

; DI int crow(int i, int h) { return (i & 3) + 8 * (i >> 2) + 4 * h; }
; DI const float* xrow(CP p, const Ptrs& w, int l, int tok) {
;   int b = tok / TPB, i = tok - b * TPB;
;   if (l == 0) return i < CTXL ? p.in[2] + (size_t)(b * CTXL + i) * DM : p.in[0] + (size_t)(b * 8192 + i - CTXL) * DM;
;   return i < CTXL ? w.xc1 + (size_t)(b * CTXL + i) * DM : p.out + (size_t)(b * 8192 + i - CTXL) * DM;
; DI void phase_out(CP p, const Ptrs& w, int l, bf16_t* sA, bf16_t* sB) {
;     ...
;         int col = n0 + wn * 64 + ni * 32 + r;
;         float gt = gate[col];
; #pragma unroll
;         for (int i = 0; i < 16; ++i) {
;           int ii = ib + wm * 64 + mi * 32 + crow(i, h);
;           const float* src = xrow(p, w, l, b * TPB + ii);
;           float* dstp = isctx ? w.xc1 + (size_t)(b * CTXL + ii) * DM : p.out + (size_t)(b * 8192 + ii - CTXL) * DM;
;           dstp[col] = src[col] + gt * acc[mi][ni][i];
.LBB0_991:
	v_ashrrev_i32_e32 v49, 31, v48
	v_lshlrev_b64 v[48:49], 13, v[48:49]
	v_lshl_add_u64 v[48:49], v[74:75], 0, v[48:49]
	v_lshl_add_u64 v[48:49], v[48:49], 0, v[66:67]
	v_add_u32_e32 v74, s39, v76
	v_ashrrev_i32_e32 v75, 31, v74
	v_lshlrev_b64 v[74:75], 13, v[74:75]
	v_lshl_add_u64 v[74:75], s[4:5], 0, v[74:75]
	v_lshl_add_u64 v[74:75], v[74:75], 0, v[66:67]
	s_mov_b64 s[10:11], -1
	s_and_b64 vcc, exec, s[40:41]
	s_waitcnt vmcnt(31)
	v_fma_f32 v48, v50, v90, v196
	v_or_b32_e32 v50, v92, v181
	global_store_dword v[74:75], v48, off
	v_add_u32_e32 v48, s38, v50
	v_mul_hi_i32 v49, v48, s0
	v_lshrrev_b32_e32 v76, 31, v49
	v_ashrrev_i32_e32 v49, 11, v49
	v_add_u32_e32 v99, v49, v76
	v_mad_i32_i24 v100, v99, s1, v48
	v_cmp_lt_i32_e64 s[48:49], s37, v100
	s_cbranch_vccnz .LBB0_997
	s_and_saveexec_b64 s[10:11], s[48:49]
	s_xor_b64 s[10:11], exec, s[10:11]
	v_lshlrev_b32_e32 v48, 13, v99
	s_movk_i32 s50, 0xff00
	v_add3_u32 v48, v48, v100, s50
	s_or_saveexec_b64 s[10:11], s[10:11]
	v_mov_b64_e32 v[76:77], s[76:77]
	s_xor_b64 exec, exec, s[10:11]
	v_lshl_add_u32 v48, v99, 8, v100
	v_mov_b64_e32 v[76:77], s[12:13]
	s_or_b64 exec, exec, s[10:11]
	s_mov_b64 s[10:11], 0

; DI int crow(int i, int h) { return (i & 3) + 8 * (i >> 2) + 4 * h; }
; DI const float* xrow(CP p, const Ptrs& w, int l, int tok) {
;   int b = tok / TPB, i = tok - b * TPB;
;   if (l == 0) return i < CTXL ? p.in[2] + (size_t)(b * CTXL + i) * DM : p.in[0] + (size_t)(b * 8192 + i - CTXL) * DM;
;   return i < CTXL ? w.xc1 + (size_t)(b * CTXL + i) * DM : p.out + (size_t)(b * 8192 + i - CTXL) * DM;
; DI void phase_out(CP p, const Ptrs& w, int l, bf16_t* sA, bf16_t* sB) {
;     ...
;         int col = n0 + wn * 64 + ni * 32 + r;
;         float gt = gate[col];
; #pragma unroll
;         for (int i = 0; i < 16; ++i) {
;           int ii = ib + wm * 64 + mi * 32 + crow(i, h);
;           const float* src = xrow(p, w, l, b * TPB + ii);
;           float* dstp = isctx ? w.xc1 + (size_t)(b * CTXL + ii) * DM : p.out + (size_t)(b * 8192 + ii - CTXL) * DM;
;           dstp[col] = src[col] + gt * acc[mi][ni][i];
.LBB0_1003:
	v_ashrrev_i32_e32 v49, 31, v48
	v_lshlrev_b64 v[48:49], 13, v[48:49]
	v_lshl_add_u64 v[48:49], v[76:77], 0, v[48:49]
	v_lshl_add_u64 v[48:49], v[48:49], 0, v[66:67]
	v_add_u32_e32 v76, s39, v50
	v_ashrrev_i32_e32 v77, 31, v76
	v_lshlrev_b64 v[76:77], 13, v[76:77]
	v_lshl_add_u64 v[76:77], s[4:5], 0, v[76:77]
	v_or_b32_e32 v78, v92, v182
	s_mov_b64 s[10:11], -1
	s_and_b64 vcc, exec, s[40:41]
	s_waitcnt vmcnt(31)
	v_fma_f32 v48, v51, v90, v197
	v_lshl_add_u64 v[50:51], v[76:77], 0, v[66:67]
	global_store_dword v[50:51], v48, off
	v_add_u32_e32 v48, s38, v78
	v_mul_hi_i32 v49, v48, s0
	v_lshrrev_b32_e32 v76, 31, v49
	v_ashrrev_i32_e32 v49, 11, v49
	v_add_u32_e32 v101, v49, v76
	v_mad_i32_i24 v102, v101, s1, v48
	v_cmp_lt_i32_e64 s[50:51], s37, v102
	s_cbranch_vccnz .LBB0_1009
	s_and_saveexec_b64 s[10:11], s[50:51]
	s_xor_b64 s[10:11], exec, s[10:11]
	v_lshlrev_b32_e32 v48, 13, v101
	s_movk_i32 s52, 0xff00
	v_add3_u32 v48, v48, v102, s52
	s_or_saveexec_b64 s[10:11], s[10:11]
	v_mov_b64_e32 v[76:77], s[76:77]
	s_xor_b64 exec, exec, s[10:11]
	v_lshl_add_u32 v48, v101, 8, v102
	v_mov_b64_e32 v[76:77], s[12:13]
	s_or_b64 exec, exec, s[10:11]
	s_mov_b64 s[10:11], 0

; DI int crow(int i, int h) { return (i & 3) + 8 * (i >> 2) + 4 * h; }
; DI const float* xrow(CP p, const Ptrs& w, int l, int tok) {
;   int b = tok / TPB, i = tok - b * TPB;
;   if (l == 0) return i < CTXL ? p.in[2] + (size_t)(b * CTXL + i) * DM : p.in[0] + (size_t)(b * 8192 + i - CTXL) * DM;
;   return i < CTXL ? w.xc1 + (size_t)(b * CTXL + i) * DM : p.out + (size_t)(b * 8192 + i - CTXL) * DM;
; DI void phase_out(CP p, const Ptrs& w, int l, bf16_t* sA, bf16_t* sB) {
;     ...
;         int col = n0 + wn * 64 + ni * 32 + r;
;         float gt = gate[col];
; #pragma unroll
;         for (int i = 0; i < 16; ++i) {
;           int ii = ib + wm * 64 + mi * 32 + crow(i, h);
;           const float* src = xrow(p, w, l, b * TPB + ii);
;           float* dstp = isctx ? w.xc1 + (size_t)(b * CTXL + ii) * DM : p.out + (size_t)(b * 8192 + ii - CTXL) * DM;
;           dstp[col] = src[col] + gt * acc[mi][ni][i];
.LBB0_1015:
	v_ashrrev_i32_e32 v49, 31, v48
	v_lshlrev_b64 v[48:49], 13, v[48:49]
	v_lshl_add_u64 v[48:49], v[76:77], 0, v[48:49]
	v_lshl_add_u64 v[48:49], v[48:49], 0, v[66:67]
	v_add_u32_e32 v76, s39, v78
	v_ashrrev_i32_e32 v77, 31, v76
	v_lshlrev_b64 v[76:77], 13, v[76:77]
	v_lshl_add_u64 v[76:77], s[4:5], 0, v[76:77]
	v_lshl_add_u64 v[76:77], v[76:77], 0, v[66:67]
	s_mov_b64 s[10:11], -1
	s_and_b64 vcc, exec, s[40:41]
	s_waitcnt vmcnt(31)
	v_fma_f32 v48, v52, v90, v198
	v_or_b32_e32 v52, v92, v183
	global_store_dword v[76:77], v48, off
	v_add_u32_e32 v48, s38, v52
	v_mul_hi_i32 v49, v48, s0
	v_lshrrev_b32_e32 v78, 31, v49
	v_ashrrev_i32_e32 v49, 11, v49
	v_add_u32_e32 v103, v49, v78
	v_mad_i32_i24 v104, v103, s1, v48
	v_cmp_lt_i32_e64 s[52:53], s37, v104
	s_cbranch_vccnz .LBB0_1021
	s_and_saveexec_b64 s[10:11], s[52:53]
	s_xor_b64 s[10:11], exec, s[10:11]
	v_lshlrev_b32_e32 v48, 13, v103
	s_movk_i32 s54, 0xff00
	v_add3_u32 v48, v48, v104, s54
	s_or_saveexec_b64 s[10:11], s[10:11]
	v_mov_b64_e32 v[78:79], s[76:77]
	s_xor_b64 exec, exec, s[10:11]
	v_lshl_add_u32 v48, v103, 8, v104
	v_mov_b64_e32 v[78:79], s[12:13]
	s_or_b64 exec, exec, s[10:11]
	s_mov_b64 s[10:11], 0

; DI int crow(int i, int h) { return (i & 3) + 8 * (i >> 2) + 4 * h; }
; DI const float* xrow(CP p, const Ptrs& w, int l, int tok) {
;   int b = tok / TPB, i = tok - b * TPB;
;   if (l == 0) return i < CTXL ? p.in[2] + (size_t)(b * CTXL + i) * DM : p.in[0] + (size_t)(b * 8192 + i - CTXL) * DM;
;   return i < CTXL ? w.xc1 + (size_t)(b * CTXL + i) * DM : p.out + (size_t)(b * 8192 + i - CTXL) * DM;
; DI void phase_out(CP p, const Ptrs& w, int l, bf16_t* sA, bf16_t* sB) {
;     ...
;         int col = n0 + wn * 64 + ni * 32 + r;
;         float gt = gate[col];
; #pragma unroll
;         for (int i = 0; i < 16; ++i) {
;           int ii = ib + wm * 64 + mi * 32 + crow(i, h);
;           const float* src = xrow(p, w, l, b * TPB + ii);
;           float* dstp = isctx ? w.xc1 + (size_t)(b * CTXL + ii) * DM : p.out + (size_t)(b * 8192 + ii - CTXL) * DM;
;           dstp[col] = src[col] + gt * acc[mi][ni][i];
.LBB0_1027:
	v_ashrrev_i32_e32 v49, 31, v48
	v_lshlrev_b64 v[48:49], 13, v[48:49]
	v_lshl_add_u64 v[48:49], v[78:79], 0, v[48:49]
	v_lshl_add_u64 v[48:49], v[48:49], 0, v[66:67]
	v_add_u32_e32 v78, s39, v52
	v_ashrrev_i32_e32 v79, 31, v78
	v_lshlrev_b64 v[78:79], 13, v[78:79]
	v_lshl_add_u64 v[78:79], s[4:5], 0, v[78:79]
	v_or_b32_e32 v80, v92, v184
	s_mov_b64 s[10:11], -1
	s_and_b64 vcc, exec, s[40:41]
	s_waitcnt vmcnt(31)
	v_fma_f32 v48, v53, v90, v199
	v_lshl_add_u64 v[52:53], v[78:79], 0, v[66:67]
	global_store_dword v[52:53], v48, off
	v_add_u32_e32 v48, s38, v80
	v_mul_hi_i32 v49, v48, s0
	v_lshrrev_b32_e32 v78, 31, v49
	v_ashrrev_i32_e32 v49, 11, v49
	v_add_u32_e32 v105, v49, v78
	v_mad_i32_i24 v106, v105, s1, v48
	v_cmp_lt_i32_e64 s[54:55], s37, v106
	s_cbranch_vccnz .LBB0_1033
	s_and_saveexec_b64 s[10:11], s[54:55]
	s_xor_b64 s[10:11], exec, s[10:11]
	v_lshlrev_b32_e32 v48, 13, v105
	s_movk_i32 s56, 0xff00
	v_add3_u32 v48, v48, v106, s56
	s_or_saveexec_b64 s[10:11], s[10:11]
	v_mov_b64_e32 v[78:79], s[76:77]
	s_xor_b64 exec, exec, s[10:11]
	v_lshl_add_u32 v48, v105, 8, v106
	v_mov_b64_e32 v[78:79], s[12:13]
	s_or_b64 exec, exec, s[10:11]
	s_mov_b64 s[10:11], 0

; DI int crow(int i, int h) { return (i & 3) + 8 * (i >> 2) + 4 * h; }
; DI const float* xrow(CP p, const Ptrs& w, int l, int tok) {
;   int b = tok / TPB, i = tok - b * TPB;
;   if (l == 0) return i < CTXL ? p.in[2] + (size_t)(b * CTXL + i) * DM : p.in[0] + (size_t)(b * 8192 + i - CTXL) * DM;
;   return i < CTXL ? w.xc1 + (size_t)(b * CTXL + i) * DM : p.out + (size_t)(b * 8192 + i - CTXL) * DM;
; DI void phase_out(CP p, const Ptrs& w, int l, bf16_t* sA, bf16_t* sB) {
;     ...
;         int col = n0 + wn * 64 + ni * 32 + r;
;         float gt = gate[col];
; #pragma unroll
;         for (int i = 0; i < 16; ++i) {
;           int ii = ib + wm * 64 + mi * 32 + crow(i, h);
;           const float* src = xrow(p, w, l, b * TPB + ii);
;           float* dstp = isctx ? w.xc1 + (size_t)(b * CTXL + ii) * DM : p.out + (size_t)(b * 8192 + ii - CTXL) * DM;
;           dstp[col] = src[col] + gt * acc[mi][ni][i];
.LBB0_1039:
	v_ashrrev_i32_e32 v49, 31, v48
	v_lshlrev_b64 v[48:49], 13, v[48:49]
	v_lshl_add_u64 v[48:49], v[78:79], 0, v[48:49]
	v_lshl_add_u64 v[48:49], v[48:49], 0, v[66:67]
	v_add_u32_e32 v78, s39, v80
	v_ashrrev_i32_e32 v79, 31, v78
	v_lshlrev_b64 v[78:79], 13, v[78:79]
	v_lshl_add_u64 v[78:79], s[4:5], 0, v[78:79]
	v_lshl_add_u64 v[78:79], v[78:79], 0, v[66:67]
	s_mov_b64 s[10:11], -1
	s_and_b64 vcc, exec, s[40:41]
	s_waitcnt vmcnt(31)
	v_fma_f32 v48, v54, v90, v200
	v_or_b32_e32 v54, v92, v185
	global_store_dword v[78:79], v48, off
	v_add_u32_e32 v48, s38, v54
	v_mul_hi_i32 v49, v48, s0
	v_lshrrev_b32_e32 v80, 31, v49
	v_ashrrev_i32_e32 v49, 11, v49
	v_add_u32_e32 v107, v49, v80
	v_mad_i32_i24 v108, v107, s1, v48
	v_cmp_lt_i32_e64 s[56:57], s37, v108
	s_cbranch_vccnz .LBB0_1045
	s_and_saveexec_b64 s[10:11], s[56:57]
	s_xor_b64 s[10:11], exec, s[10:11]
	v_lshlrev_b32_e32 v48, 13, v107
	s_movk_i32 s58, 0xff00
	v_add3_u32 v48, v48, v108, s58
	s_or_saveexec_b64 s[10:11], s[10:11]
	v_mov_b64_e32 v[80:81], s[76:77]
	s_xor_b64 exec, exec, s[10:11]
	v_lshl_add_u32 v48, v107, 8, v108
	v_mov_b64_e32 v[80:81], s[12:13]
	s_or_b64 exec, exec, s[10:11]
	s_mov_b64 s[10:11], 0

; DI int crow(int i, int h) { return (i & 3) + 8 * (i >> 2) + 4 * h; }
; DI const float* xrow(CP p, const Ptrs& w, int l, int tok) {
;   int b = tok / TPB, i = tok - b * TPB;
;   if (l == 0) return i < CTXL ? p.in[2] + (size_t)(b * CTXL + i) * DM : p.in[0] + (size_t)(b * 8192 + i - CTXL) * DM;
;   return i < CTXL ? w.xc1 + (size_t)(b * CTXL + i) * DM : p.out + (size_t)(b * 8192 + i - CTXL) * DM;
; DI void phase_out(CP p, const Ptrs& w, int l, bf16_t* sA, bf16_t* sB) {
;     ...
;         int col = n0 + wn * 64 + ni * 32 + r;
;         float gt = gate[col];
; #pragma unroll
;         for (int i = 0; i < 16; ++i) {
;           int ii = ib + wm * 64 + mi * 32 + crow(i, h);
;           const float* src = xrow(p, w, l, b * TPB + ii);
;           float* dstp = isctx ? w.xc1 + (size_t)(b * CTXL + ii) * DM : p.out + (size_t)(b * 8192 + ii - CTXL) * DM;
;           dstp[col] = src[col] + gt * acc[mi][ni][i];
.LBB0_1051:
	v_ashrrev_i32_e32 v49, 31, v48
	v_lshlrev_b64 v[48:49], 13, v[48:49]
	v_lshl_add_u64 v[48:49], v[80:81], 0, v[48:49]
	v_lshl_add_u64 v[48:49], v[48:49], 0, v[66:67]
	v_add_u32_e32 v80, s39, v54
	v_ashrrev_i32_e32 v81, 31, v80
	v_lshlrev_b64 v[80:81], 13, v[80:81]
	v_lshl_add_u64 v[80:81], s[4:5], 0, v[80:81]
	v_or_b32_e32 v82, v92, v186
	s_mov_b64 s[10:11], -1
	s_and_b64 vcc, exec, s[40:41]
	s_waitcnt vmcnt(31)
	v_fma_f32 v48, v55, v90, v201
	v_lshl_add_u64 v[54:55], v[80:81], 0, v[66:67]
	global_store_dword v[54:55], v48, off
	v_add_u32_e32 v48, s38, v82
	v_mul_hi_i32 v49, v48, s0
	v_lshrrev_b32_e32 v80, 31, v49
	v_ashrrev_i32_e32 v49, 11, v49
	v_add_u32_e32 v109, v49, v80
	v_mad_i32_i24 v110, v109, s1, v48
	v_cmp_lt_i32_e64 s[58:59], s37, v110
	s_cbranch_vccnz .LBB0_1057
	s_and_saveexec_b64 s[10:11], s[58:59]
	s_xor_b64 s[10:11], exec, s[10:11]
	v_lshlrev_b32_e32 v48, 13, v109
	s_movk_i32 s60, 0xff00
	v_add3_u32 v48, v48, v110, s60
	s_or_saveexec_b64 s[10:11], s[10:11]
	v_mov_b64_e32 v[80:81], s[76:77]
	s_xor_b64 exec, exec, s[10:11]
	v_lshl_add_u32 v48, v109, 8, v110
	v_mov_b64_e32 v[80:81], s[12:13]
	s_or_b64 exec, exec, s[10:11]
	s_mov_b64 s[10:11], 0

; DI int crow(int i, int h) { return (i & 3) + 8 * (i >> 2) + 4 * h; }
; DI const float* xrow(CP p, const Ptrs& w, int l, int tok) {
;   int b = tok / TPB, i = tok - b * TPB;
;   if (l == 0) return i < CTXL ? p.in[2] + (size_t)(b * CTXL + i) * DM : p.in[0] + (size_t)(b * 8192 + i - CTXL) * DM;
;   return i < CTXL ? w.xc1 + (size_t)(b * CTXL + i) * DM : p.out + (size_t)(b * 8192 + i - CTXL) * DM;
; DI void phase_out(CP p, const Ptrs& w, int l, bf16_t* sA, bf16_t* sB) {
;     ...
;         int col = n0 + wn * 64 + ni * 32 + r;
;         float gt = gate[col];
; #pragma unroll
;         for (int i = 0; i < 16; ++i) {
;           int ii = ib + wm * 64 + mi * 32 + crow(i, h);
;           const float* src = xrow(p, w, l, b * TPB + ii);
;           float* dstp = isctx ? w.xc1 + (size_t)(b * CTXL + ii) * DM : p.out + (size_t)(b * 8192 + ii - CTXL) * DM;
;           dstp[col] = src[col] + gt * acc[mi][ni][i];
.LBB0_1063:
	v_ashrrev_i32_e32 v49, 31, v48
	v_lshlrev_b64 v[48:49], 13, v[48:49]
	v_lshl_add_u64 v[48:49], v[80:81], 0, v[48:49]
	v_lshl_add_u64 v[48:49], v[48:49], 0, v[66:67]
	v_add_u32_e32 v80, s39, v82
	v_ashrrev_i32_e32 v81, 31, v80
	v_lshlrev_b64 v[80:81], 13, v[80:81]
	v_lshl_add_u64 v[80:81], s[4:5], 0, v[80:81]
	v_lshl_add_u64 v[80:81], v[80:81], 0, v[66:67]
	s_mov_b64 s[10:11], -1
	s_and_b64 vcc, exec, s[40:41]
	s_waitcnt vmcnt(31)
	v_fma_f32 v48, v56, v90, v202
	v_or_b32_e32 v56, v92, v187
	global_store_dword v[80:81], v48, off
	v_add_u32_e32 v48, s38, v56
	v_mul_hi_i32 v49, v48, s0
	v_lshrrev_b32_e32 v82, 31, v49
	v_ashrrev_i32_e32 v49, 11, v49
	v_add_u32_e32 v111, v49, v82
	v_mad_i32_i24 v112, v111, s1, v48
	v_cmp_lt_i32_e64 s[60:61], s37, v112
	s_cbranch_vccnz .LBB0_1069
	s_and_saveexec_b64 s[10:11], s[60:61]
	s_xor_b64 s[10:11], exec, s[10:11]
	v_lshlrev_b32_e32 v48, 13, v111
	s_movk_i32 s62, 0xff00
	v_add3_u32 v48, v48, v112, s62
	s_or_saveexec_b64 s[10:11], s[10:11]
	v_mov_b64_e32 v[82:83], s[76:77]
	s_xor_b64 exec, exec, s[10:11]
	v_lshl_add_u32 v48, v111, 8, v112
	v_mov_b64_e32 v[82:83], s[12:13]
	s_or_b64 exec, exec, s[10:11]
	s_mov_b64 s[10:11], 0

; DI int crow(int i, int h) { return (i & 3) + 8 * (i >> 2) + 4 * h; }
; DI const float* xrow(CP p, const Ptrs& w, int l, int tok) {
;   int b = tok / TPB, i = tok - b * TPB;
;   if (l == 0) return i < CTXL ? p.in[2] + (size_t)(b * CTXL + i) * DM : p.in[0] + (size_t)(b * 8192 + i - CTXL) * DM;
;   return i < CTXL ? w.xc1 + (size_t)(b * CTXL + i) * DM : p.out + (size_t)(b * 8192 + i - CTXL) * DM;
; DI void phase_out(CP p, const Ptrs& w, int l, bf16_t* sA, bf16_t* sB) {
;     ...
;         int col = n0 + wn * 64 + ni * 32 + r;
;         float gt = gate[col];
; #pragma unroll
;         for (int i = 0; i < 16; ++i) {
;           int ii = ib + wm * 64 + mi * 32 + crow(i, h);
;           const float* src = xrow(p, w, l, b * TPB + ii);
;           float* dstp = isctx ? w.xc1 + (size_t)(b * CTXL + ii) * DM : p.out + (size_t)(b * 8192 + ii - CTXL) * DM;
;           dstp[col] = src[col] + gt * acc[mi][ni][i];
.LBB0_1075:
	v_ashrrev_i32_e32 v49, 31, v48
	v_lshlrev_b64 v[48:49], 13, v[48:49]
	v_lshl_add_u64 v[48:49], v[82:83], 0, v[48:49]
	v_lshl_add_u64 v[48:49], v[48:49], 0, v[66:67]
	v_add_u32_e32 v82, s39, v56
	v_ashrrev_i32_e32 v83, 31, v82
	v_lshlrev_b64 v[82:83], 13, v[82:83]
	v_lshl_add_u64 v[82:83], s[4:5], 0, v[82:83]
	v_or_b32_e32 v84, v92, v188
	s_mov_b64 s[10:11], -1
	s_and_b64 vcc, exec, s[40:41]
	s_waitcnt vmcnt(31)
	v_fma_f32 v48, v57, v90, v203
	v_lshl_add_u64 v[56:57], v[82:83], 0, v[66:67]
	global_store_dword v[56:57], v48, off
	v_add_u32_e32 v48, s38, v84
	v_mul_hi_i32 v49, v48, s0
	v_lshrrev_b32_e32 v82, 31, v49
	v_ashrrev_i32_e32 v49, 11, v49
	v_add_u32_e32 v113, v49, v82
	v_mad_i32_i24 v114, v113, s1, v48
	v_cmp_lt_i32_e64 s[62:63], s37, v114
	s_cbranch_vccnz .LBB0_1081
	s_and_saveexec_b64 s[10:11], s[62:63]
	s_xor_b64 s[10:11], exec, s[10:11]
	v_lshlrev_b32_e32 v48, 13, v113
	s_movk_i32 s64, 0xff00
	v_add3_u32 v48, v48, v114, s64
	s_or_saveexec_b64 s[10:11], s[10:11]
	v_mov_b64_e32 v[82:83], s[76:77]
	s_xor_b64 exec, exec, s[10:11]
	v_lshl_add_u32 v48, v113, 8, v114
	v_mov_b64_e32 v[82:83], s[12:13]
	s_or_b64 exec, exec, s[10:11]
	s_mov_b64 s[10:11], 0

; DI int crow(int i, int h) { return (i & 3) + 8 * (i >> 2) + 4 * h; }
; DI const float* xrow(CP p, const Ptrs& w, int l, int tok) {
;   int b = tok / TPB, i = tok - b * TPB;
;   if (l == 0) return i < CTXL ? p.in[2] + (size_t)(b * CTXL + i) * DM : p.in[0] + (size_t)(b * 8192 + i - CTXL) * DM;
;   return i < CTXL ? w.xc1 + (size_t)(b * CTXL + i) * DM : p.out + (size_t)(b * 8192 + i - CTXL) * DM;
; DI void phase_out(CP p, const Ptrs& w, int l, bf16_t* sA, bf16_t* sB) {
;     ...
;         int col = n0 + wn * 64 + ni * 32 + r;
;         float gt = gate[col];
; #pragma unroll
;         for (int i = 0; i < 16; ++i) {
;           int ii = ib + wm * 64 + mi * 32 + crow(i, h);
;           const float* src = xrow(p, w, l, b * TPB + ii);
;           float* dstp = isctx ? w.xc1 + (size_t)(b * CTXL + ii) * DM : p.out + (size_t)(b * 8192 + ii - CTXL) * DM;
;           dstp[col] = src[col] + gt * acc[mi][ni][i];
.LBB0_1087:
	v_ashrrev_i32_e32 v49, 31, v48
	v_lshlrev_b64 v[48:49], 13, v[48:49]
	v_lshl_add_u64 v[48:49], v[82:83], 0, v[48:49]
	v_lshl_add_u64 v[48:49], v[48:49], 0, v[66:67]
	v_add_u32_e32 v82, s39, v84
	v_ashrrev_i32_e32 v83, 31, v82
	v_lshlrev_b64 v[82:83], 13, v[82:83]
	v_lshl_add_u64 v[82:83], s[4:5], 0, v[82:83]
	v_lshl_add_u64 v[82:83], v[82:83], 0, v[66:67]
	s_mov_b64 s[10:11], -1
	s_and_b64 vcc, exec, s[40:41]
	s_waitcnt vmcnt(31)
	v_fma_f32 v48, v58, v90, v204
	v_or_b32_e32 v58, v92, v189
	global_store_dword v[82:83], v48, off
	v_add_u32_e32 v48, s38, v58
	v_mul_hi_i32 v49, v48, s0
	v_lshrrev_b32_e32 v84, 31, v49
	v_ashrrev_i32_e32 v49, 11, v49
	v_add_u32_e32 v115, v49, v84
	v_mad_i32_i24 v116, v115, s1, v48
	v_cmp_lt_i32_e64 s[64:65], s37, v116
	s_cbranch_vccnz .LBB0_1093
	s_and_saveexec_b64 s[10:11], s[64:65]
	s_xor_b64 s[10:11], exec, s[10:11]
	v_lshlrev_b32_e32 v48, 13, v115
	s_movk_i32 s66, 0xff00
	v_add3_u32 v48, v48, v116, s66
	s_or_saveexec_b64 s[10:11], s[10:11]
	v_mov_b64_e32 v[84:85], s[76:77]
	s_xor_b64 exec, exec, s[10:11]
	v_lshl_add_u32 v48, v115, 8, v116
	v_mov_b64_e32 v[84:85], s[12:13]
	s_or_b64 exec, exec, s[10:11]
	s_mov_b64 s[10:11], 0

; DI int crow(int i, int h) { return (i & 3) + 8 * (i >> 2) + 4 * h; }
; DI const float* xrow(CP p, const Ptrs& w, int l, int tok) {
;   int b = tok / TPB, i = tok - b * TPB;
;   if (l == 0) return i < CTXL ? p.in[2] + (size_t)(b * CTXL + i) * DM : p.in[0] + (size_t)(b * 8192 + i - CTXL) * DM;
;   return i < CTXL ? w.xc1 + (size_t)(b * CTXL + i) * DM : p.out + (size_t)(b * 8192 + i - CTXL) * DM;
; DI void phase_out(CP p, const Ptrs& w, int l, bf16_t* sA, bf16_t* sB) {
;     ...
;         int col = n0 + wn * 64 + ni * 32 + r;
;         float gt = gate[col];
; #pragma unroll
;         for (int i = 0; i < 16; ++i) {
;           int ii = ib + wm * 64 + mi * 32 + crow(i, h);
;           const float* src = xrow(p, w, l, b * TPB + ii);
;           float* dstp = isctx ? w.xc1 + (size_t)(b * CTXL + ii) * DM : p.out + (size_t)(b * 8192 + ii - CTXL) * DM;
;           dstp[col] = src[col] + gt * acc[mi][ni][i];
.LBB0_1099:
	v_ashrrev_i32_e32 v49, 31, v48
	v_lshlrev_b64 v[48:49], 13, v[48:49]
	v_lshl_add_u64 v[48:49], v[84:85], 0, v[48:49]
	v_lshl_add_u64 v[48:49], v[48:49], 0, v[66:67]
	v_add_u32_e32 v84, s39, v58
	v_ashrrev_i32_e32 v85, 31, v84
	v_lshlrev_b64 v[84:85], 13, v[84:85]
	v_lshl_add_u64 v[84:85], s[4:5], 0, v[84:85]
	v_or_b32_e32 v86, v92, v190
	s_mov_b64 s[10:11], -1
	s_and_b64 vcc, exec, s[40:41]
	s_waitcnt vmcnt(31)
	v_fma_f32 v48, v59, v90, v205
	v_lshl_add_u64 v[58:59], v[84:85], 0, v[66:67]
	global_store_dword v[58:59], v48, off
	v_add_u32_e32 v48, s38, v86
	v_mul_hi_i32 v49, v48, s0
	v_lshrrev_b32_e32 v84, 31, v49
	v_ashrrev_i32_e32 v49, 11, v49
	v_add_u32_e32 v117, v49, v84
	v_mad_i32_i24 v118, v117, s1, v48
	v_cmp_lt_i32_e64 s[66:67], s37, v118
	s_cbranch_vccnz .LBB0_1105
	s_and_saveexec_b64 s[10:11], s[66:67]
	s_xor_b64 s[10:11], exec, s[10:11]
	v_lshlrev_b32_e32 v48, 13, v117
	s_movk_i32 s68, 0xff00
	v_add3_u32 v48, v48, v118, s68
	s_or_saveexec_b64 s[10:11], s[10:11]
	v_mov_b64_e32 v[84:85], s[76:77]
	s_xor_b64 exec, exec, s[10:11]
	v_lshl_add_u32 v48, v117, 8, v118
	v_mov_b64_e32 v[84:85], s[12:13]
	s_or_b64 exec, exec, s[10:11]
	s_mov_b64 s[10:11], 0

; DI int crow(int i, int h) { return (i & 3) + 8 * (i >> 2) + 4 * h; }
; DI const float* xrow(CP p, const Ptrs& w, int l, int tok) {
;   int b = tok / TPB, i = tok - b * TPB;
;   if (l == 0) return i < CTXL ? p.in[2] + (size_t)(b * CTXL + i) * DM : p.in[0] + (size_t)(b * 8192 + i - CTXL) * DM;
;   return i < CTXL ? w.xc1 + (size_t)(b * CTXL + i) * DM : p.out + (size_t)(b * 8192 + i - CTXL) * DM;
; DI void phase_out(CP p, const Ptrs& w, int l, bf16_t* sA, bf16_t* sB) {
;     ...
;         int col = n0 + wn * 64 + ni * 32 + r;
;         float gt = gate[col];
; #pragma unroll
;         for (int i = 0; i < 16; ++i) {
;           int ii = ib + wm * 64 + mi * 32 + crow(i, h);
;           const float* src = xrow(p, w, l, b * TPB + ii);
;           float* dstp = isctx ? w.xc1 + (size_t)(b * CTXL + ii) * DM : p.out + (size_t)(b * 8192 + ii - CTXL) * DM;
;           dstp[col] = src[col] + gt * acc[mi][ni][i];
.LBB0_1111:
	v_ashrrev_i32_e32 v49, 31, v48
	v_lshlrev_b64 v[48:49], 13, v[48:49]
	v_lshl_add_u64 v[48:49], v[84:85], 0, v[48:49]
	v_lshl_add_u64 v[48:49], v[48:49], 0, v[66:67]
	v_add_u32_e32 v84, s39, v86
	v_ashrrev_i32_e32 v85, 31, v84
	v_lshlrev_b64 v[84:85], 13, v[84:85]
	v_lshl_add_u64 v[84:85], s[4:5], 0, v[84:85]
	v_lshl_add_u64 v[84:85], v[84:85], 0, v[66:67]
	s_mov_b64 s[10:11], -1
	s_and_b64 vcc, exec, s[40:41]
	s_waitcnt vmcnt(31)
	v_fma_f32 v48, v60, v90, v206
	v_or_b32_e32 v60, v92, v191
	global_store_dword v[84:85], v48, off
	v_add_u32_e32 v48, s38, v60
	v_mul_hi_i32 v49, v48, s0
	v_lshrrev_b32_e32 v86, 31, v49
	v_ashrrev_i32_e32 v49, 11, v49
	v_add_u32_e32 v119, v49, v86
	v_mad_i32_i24 v120, v119, s1, v48
	v_cmp_lt_i32_e64 s[68:69], s37, v120
	s_cbranch_vccnz .LBB0_1117
	s_and_saveexec_b64 s[10:11], s[68:69]
	s_xor_b64 s[10:11], exec, s[10:11]
	v_lshlrev_b32_e32 v48, 13, v119
	s_movk_i32 s70, 0xff00
	v_add3_u32 v48, v48, v120, s70
	s_or_saveexec_b64 s[10:11], s[10:11]
	v_mov_b64_e32 v[86:87], s[76:77]
	s_xor_b64 exec, exec, s[10:11]
	v_lshl_add_u32 v48, v119, 8, v120
	v_mov_b64_e32 v[86:87], s[12:13]
	s_or_b64 exec, exec, s[10:11]
	s_mov_b64 s[10:11], 0

; DI int crow(int i, int h) { return (i & 3) + 8 * (i >> 2) + 4 * h; }
; DI const float* xrow(CP p, const Ptrs& w, int l, int tok) {
;   int b = tok / TPB, i = tok - b * TPB;
;   if (l == 0) return i < CTXL ? p.in[2] + (size_t)(b * CTXL + i) * DM : p.in[0] + (size_t)(b * 8192 + i - CTXL) * DM;
;   return i < CTXL ? w.xc1 + (size_t)(b * CTXL + i) * DM : p.out + (size_t)(b * 8192 + i - CTXL) * DM;
; DI void phase_out(CP p, const Ptrs& w, int l, bf16_t* sA, bf16_t* sB) {
;     ...
;         int col = n0 + wn * 64 + ni * 32 + r;
;         float gt = gate[col];
; #pragma unroll
;         for (int i = 0; i < 16; ++i) {
;           int ii = ib + wm * 64 + mi * 32 + crow(i, h);
;           const float* src = xrow(p, w, l, b * TPB + ii);
;           float* dstp = isctx ? w.xc1 + (size_t)(b * CTXL + ii) * DM : p.out + (size_t)(b * 8192 + ii - CTXL) * DM;
;           dstp[col] = src[col] + gt * acc[mi][ni][i];
.LBB0_1123:
	v_ashrrev_i32_e32 v49, 31, v48
	v_lshlrev_b64 v[48:49], 13, v[48:49]
	v_lshl_add_u64 v[48:49], v[86:87], 0, v[48:49]
	v_lshl_add_u64 v[48:49], v[48:49], 0, v[66:67]
	v_add_u32_e32 v86, s39, v60
	v_ashrrev_i32_e32 v87, 31, v86
	v_lshlrev_b64 v[86:87], 13, v[86:87]
	v_lshl_add_u64 v[86:87], s[4:5], 0, v[86:87]
	v_or_b32_e32 v88, v92, v192
	s_mov_b64 s[10:11], -1
	s_and_b64 vcc, exec, s[40:41]
	s_waitcnt vmcnt(31)
	v_fma_f32 v48, v61, v90, v207
	v_lshl_add_u64 v[60:61], v[86:87], 0, v[66:67]
	global_store_dword v[60:61], v48, off
	v_add_u32_e32 v48, s38, v88
	v_mul_hi_i32 v49, v48, s0
	v_lshrrev_b32_e32 v86, 31, v49
	v_ashrrev_i32_e32 v49, 11, v49
	v_add_u32_e32 v121, v49, v86
	v_mad_i32_i24 v122, v121, s1, v48
	v_cmp_lt_i32_e64 s[70:71], s37, v122
	s_cbranch_vccnz .LBB0_1129
	s_and_saveexec_b64 s[10:11], s[70:71]
	s_xor_b64 s[10:11], exec, s[10:11]
	v_lshlrev_b32_e32 v48, 13, v121
	s_movk_i32 s72, 0xff00
	v_add3_u32 v48, v48, v122, s72
	s_or_saveexec_b64 s[10:11], s[10:11]
	v_mov_b64_e32 v[86:87], s[76:77]
	s_xor_b64 exec, exec, s[10:11]
	v_lshl_add_u32 v48, v121, 8, v122
	v_mov_b64_e32 v[86:87], s[12:13]
	s_or_b64 exec, exec, s[10:11]
	s_mov_b64 s[10:11], 0

; DI int crow(int i, int h) { return (i & 3) + 8 * (i >> 2) + 4 * h; }
; DI const float* xrow(CP p, const Ptrs& w, int l, int tok) {
;   int b = tok / TPB, i = tok - b * TPB;
;   if (l == 0) return i < CTXL ? p.in[2] + (size_t)(b * CTXL + i) * DM : p.in[0] + (size_t)(b * 8192 + i - CTXL) * DM;
;   return i < CTXL ? w.xc1 + (size_t)(b * CTXL + i) * DM : p.out + (size_t)(b * 8192 + i - CTXL) * DM;
; DI void phase_out(CP p, const Ptrs& w, int l, bf16_t* sA, bf16_t* sB) {
;     ...
;         int col = n0 + wn * 64 + ni * 32 + r;
;         float gt = gate[col];
; #pragma unroll
;         for (int i = 0; i < 16; ++i) {
;           int ii = ib + wm * 64 + mi * 32 + crow(i, h);
;           const float* src = xrow(p, w, l, b * TPB + ii);
;           float* dstp = isctx ? w.xc1 + (size_t)(b * CTXL + ii) * DM : p.out + (size_t)(b * 8192 + ii - CTXL) * DM;
;           dstp[col] = src[col] + gt * acc[mi][ni][i];
.LBB0_1135:
	v_ashrrev_i32_e32 v49, 31, v48
	v_lshlrev_b64 v[48:49], 13, v[48:49]
	v_lshl_add_u64 v[48:49], v[86:87], 0, v[48:49]
	v_lshl_add_u64 v[48:49], v[48:49], 0, v[66:67]
	v_add_u32_e32 v86, s39, v88
	v_ashrrev_i32_e32 v87, 31, v86
	v_lshlrev_b64 v[86:87], 13, v[86:87]
	v_lshl_add_u64 v[86:87], s[4:5], 0, v[86:87]
	v_lshl_add_u64 v[86:87], v[86:87], 0, v[66:67]
	s_mov_b64 s[10:11], -1
	s_and_b64 vcc, exec, s[40:41]
	s_waitcnt vmcnt(31)
	v_fma_f32 v48, v62, v90, v208
	v_or_b32_e32 v62, v92, v193
	global_store_dword v[86:87], v48, off
	v_add_u32_e32 v48, s38, v62
	v_mul_hi_i32 v49, v48, s0
	v_lshrrev_b32_e32 v88, 31, v49
	v_ashrrev_i32_e32 v49, 11, v49
	v_add_u32_e32 v123, v49, v88
	v_mad_i32_i24 v124, v123, s1, v48
	v_cmp_lt_i32_e64 s[72:73], s37, v124
	s_cbranch_vccnz .LBB0_1141
	s_and_saveexec_b64 s[10:11], s[72:73]
	s_xor_b64 s[10:11], exec, s[10:11]
	v_lshlrev_b32_e32 v48, 13, v123
	s_movk_i32 vcc_lo, 0xff00
	v_add3_u32 v48, v48, v124, vcc_lo
	s_or_saveexec_b64 s[10:11], s[10:11]
	v_mov_b64_e32 v[88:89], s[76:77]
	s_xor_b64 exec, exec, s[10:11]
	v_lshl_add_u32 v48, v123, 8, v124
	v_mov_b64_e32 v[88:89], s[12:13]
	s_or_b64 exec, exec, s[10:11]
	s_mov_b64 s[10:11], 0

; DI int crow(int i, int h) { return (i & 3) + 8 * (i >> 2) + 4 * h; }
; DI void phase_out(CP p, const Ptrs& w, int l, bf16_t* sA, bf16_t* sB) {
;     ...
;         int col = n0 + wn * 64 + ni * 32 + r;
;         float gt = gate[col];
; #pragma unroll
;         for (int i = 0; i < 16; ++i) {
;           int ii = ib + wm * 64 + mi * 32 + crow(i, h);
;           const float* src = xrow(p, w, l, b * TPB + ii);
;           float* dstp = isctx ? w.xc1 + (size_t)(b * CTXL + ii) * DM : p.out + (size_t)(b * 8192 + ii - CTXL) * DM;
;           dstp[col] = src[col] + gt * acc[mi][ni][i];
.LBB0_1147:
	v_ashrrev_i32_e32 v49, 31, v48
	v_lshlrev_b64 v[48:49], 13, v[48:49]
	v_lshl_add_u64 v[48:49], v[88:89], 0, v[48:49]
	v_lshl_add_u64 v[48:49], v[48:49], 0, v[66:67]
	v_add_u32_e32 v48, s39, v62
	v_ashrrev_i32_e32 v49, 31, v48
	v_lshlrev_b64 v[48:49], 13, v[48:49]
	v_or_b32_e32 v126, 32, v64
	v_lshl_add_u64 v[48:49], s[4:5], 0, v[48:49]
	v_ashrrev_i32_e32 v127, 31, v126
	v_lshl_add_u64 v[88:89], v[48:49], 0, v[66:67]
	v_lshl_add_u64 v[48:49], v[126:127], 2, s[6:7]
	s_and_b64 vcc, exec, s[40:41]
	s_mov_b64 s[6:7], -1
	s_waitcnt vmcnt(31)
	v_fma_f32 v91, v63, v90, v209
	global_store_dword v[88:89], v91, off
	global_load_dword v125, v[48:49], off
	s_cbranch_vccnz .LBB0_1153
	s_and_saveexec_b64 s[6:7], s[42:43]
	s_xor_b64 s[6:7], exec, s[6:7]
	v_lshlrev_b32_e32 v62, 13, v93
	s_movk_i32 s10, 0xff00
	v_add3_u32 v62, v62, v94, s10
	s_or_saveexec_b64 s[6:7], s[6:7]
	v_mov_b64_e32 v[90:91], s[76:77]
	s_xor_b64 exec, exec, s[6:7]
	v_lshl_add_u32 v62, v93, 8, v94
	v_mov_b64_e32 v[90:91], s[12:13]
	s_or_b64 exec, exec, s[6:7]
	s_mov_b64 s[6:7], 0

; DI int crow(int i, int h) { return (i & 3) + 8 * (i >> 2) + 4 * h; }
; DI const float* xrow(CP p, const Ptrs& w, int l, int tok) {
;   int b = tok / TPB, i = tok - b * TPB;
;   if (l == 0) return i < CTXL ? p.in[2] + (size_t)(b * CTXL + i) * DM : p.in[0] + (size_t)(b * 8192 + i - CTXL) * DM;
;   return i < CTXL ? w.xc1 + (size_t)(b * CTXL + i) * DM : p.out + (size_t)(b * 8192 + i - CTXL) * DM;
; DI void phase_out(CP p, const Ptrs& w, int l, bf16_t* sA, bf16_t* sB) {
;     ...
;         int col = n0 + wn * 64 + ni * 32 + r;
;         float gt = gate[col];
; #pragma unroll
;         for (int i = 0; i < 16; ++i) {
;           int ii = ib + wm * 64 + mi * 32 + crow(i, h);
;           const float* src = xrow(p, w, l, b * TPB + ii);
;           float* dstp = isctx ? w.xc1 + (size_t)(b * CTXL + ii) * DM : p.out + (size_t)(b * 8192 + ii - CTXL) * DM;
;           dstp[col] = src[col] + gt * acc[mi][ni][i];
.LBB0_1351:
	v_ashrrev_i32_e32 v33, 31, v32
	v_lshlrev_b64 v[32:33], 13, v[32:33]
	v_lshl_add_u64 v[32:33], v[34:35], 0, v[32:33]
	v_lshl_add_u64 v[32:33], v[32:33], 0, v[66:67]
	v_add_u32_e32 v34, s39, v36
	v_ashrrev_i32_e32 v35, 31, v34
	v_lshlrev_b64 v[34:35], 13, v[34:35]
	v_lshl_add_u64 v[34:35], s[4:5], 0, v[34:35]
	v_lshl_add_u64 v[32:33], v[34:35], 0, v[66:67]
	s_mov_b64 s[6:7], -1
	s_and_b64 vcc, exec, s[40:41]
	s_waitcnt vmcnt(0)
	v_fma_f32 v36, v16, v58, v210
	v_or_b32_e32 v16, v52, v167
	v_add_u32_e32 v34, s38, v16
	v_mul_hi_i32 v35, v34, s0
	global_store_dword v[32:33], v36, off
	v_lshrrev_b32_e32 v36, 31, v35
	v_ashrrev_i32_e32 v35, 11, v35
	v_add_u32_e32 v56, v35, v36
	v_mad_i32_i24 v57, v56, s1, v34
	v_cmp_lt_i32_e64 s[44:45], s37, v57
	s_cbranch_vccnz .LBB0_1357
	s_and_saveexec_b64 s[6:7], s[44:45]
	s_xor_b64 s[6:7], exec, s[6:7]
	v_lshlrev_b32_e32 v34, 13, v56
	s_movk_i32 s10, 0xff00
	v_add3_u32 v34, v34, v57, s10
	s_or_saveexec_b64 s[6:7], s[6:7]
	v_mov_b64_e32 v[36:37], s[76:77]
	s_xor_b64 exec, exec, s[6:7]
	v_lshl_add_u32 v34, v56, 8, v57
	v_mov_b64_e32 v[36:37], s[12:13]
	s_or_b64 exec, exec, s[6:7]
	s_mov_b64 s[6:7], 0

; DI int crow(int i, int h) { return (i & 3) + 8 * (i >> 2) + 4 * h; }
; DI const float* xrow(CP p, const Ptrs& w, int l, int tok) {
;   int b = tok / TPB, i = tok - b * TPB;
;   if (l == 0) return i < CTXL ? p.in[2] + (size_t)(b * CTXL + i) * DM : p.in[0] + (size_t)(b * 8192 + i - CTXL) * DM;
;   return i < CTXL ? w.xc1 + (size_t)(b * CTXL + i) * DM : p.out + (size_t)(b * 8192 + i - CTXL) * DM;
; DI void phase_out(CP p, const Ptrs& w, int l, bf16_t* sA, bf16_t* sB) {
;     ...
;         int col = n0 + wn * 64 + ni * 32 + r;
;         float gt = gate[col];
; #pragma unroll
;         for (int i = 0; i < 16; ++i) {
;           int ii = ib + wm * 64 + mi * 32 + crow(i, h);
;           const float* src = xrow(p, w, l, b * TPB + ii);
;           float* dstp = isctx ? w.xc1 + (size_t)(b * CTXL + ii) * DM : p.out + (size_t)(b * 8192 + ii - CTXL) * DM;
;           dstp[col] = src[col] + gt * acc[mi][ni][i];
.LBB0_1363:
	v_ashrrev_i32_e32 v35, 31, v34
	v_lshlrev_b64 v[34:35], 13, v[34:35]
	v_lshl_add_u64 v[34:35], v[36:37], 0, v[34:35]
	v_lshl_add_u64 v[34:35], v[34:35], 0, v[66:67]
	v_add_u32_e32 v36, s39, v16
	v_ashrrev_i32_e32 v37, 31, v36
	v_lshlrev_b64 v[36:37], 13, v[36:37]
	v_lshl_add_u64 v[36:37], s[4:5], 0, v[36:37]
	v_or_b32_e32 v38, v52, v180
	s_mov_b64 s[6:7], -1
	s_and_b64 vcc, exec, s[40:41]
	s_waitcnt vmcnt(1)
	v_fma_f32 v34, v17, v58, v211
	v_lshl_add_u64 v[16:17], v[36:37], 0, v[66:67]
	global_store_dword v[16:17], v34, off
	v_add_u32_e32 v34, s38, v38
	v_mul_hi_i32 v35, v34, s0
	v_lshrrev_b32_e32 v36, 31, v35
	v_ashrrev_i32_e32 v35, 11, v35
	v_add_u32_e32 v59, v35, v36
	v_mad_i32_i24 v60, v59, s1, v34
	v_cmp_lt_i32_e64 s[46:47], s37, v60
	s_cbranch_vccnz .LBB0_1369
	s_and_saveexec_b64 s[6:7], s[46:47]
	s_xor_b64 s[6:7], exec, s[6:7]
	v_lshlrev_b32_e32 v34, 13, v59
	s_movk_i32 s10, 0xff00
	v_add3_u32 v34, v34, v60, s10
	s_or_saveexec_b64 s[6:7], s[6:7]
	v_mov_b64_e32 v[36:37], s[76:77]
	s_xor_b64 exec, exec, s[6:7]
	v_lshl_add_u32 v34, v59, 8, v60
	v_mov_b64_e32 v[36:37], s[12:13]
	s_or_b64 exec, exec, s[6:7]
	s_mov_b64 s[6:7], 0

; DI int crow(int i, int h) { return (i & 3) + 8 * (i >> 2) + 4 * h; }
; DI const float* xrow(CP p, const Ptrs& w, int l, int tok) {
;   int b = tok / TPB, i = tok - b * TPB;
;   if (l == 0) return i < CTXL ? p.in[2] + (size_t)(b * CTXL + i) * DM : p.in[0] + (size_t)(b * 8192 + i - CTXL) * DM;
;   return i < CTXL ? w.xc1 + (size_t)(b * CTXL + i) * DM : p.out + (size_t)(b * 8192 + i - CTXL) * DM;
; DI void phase_out(CP p, const Ptrs& w, int l, bf16_t* sA, bf16_t* sB) {
;     ...
;         int col = n0 + wn * 64 + ni * 32 + r;
;         float gt = gate[col];
; #pragma unroll
;         for (int i = 0; i < 16; ++i) {
;           int ii = ib + wm * 64 + mi * 32 + crow(i, h);
;           const float* src = xrow(p, w, l, b * TPB + ii);
;           float* dstp = isctx ? w.xc1 + (size_t)(b * CTXL + ii) * DM : p.out + (size_t)(b * 8192 + ii - CTXL) * DM;
;           dstp[col] = src[col] + gt * acc[mi][ni][i];
.LBB0_1375:
	v_ashrrev_i32_e32 v35, 31, v34
	v_lshlrev_b64 v[34:35], 13, v[34:35]
	v_lshl_add_u64 v[34:35], v[36:37], 0, v[34:35]
	v_lshl_add_u64 v[34:35], v[34:35], 0, v[66:67]
	v_add_u32_e32 v36, s39, v38
	v_ashrrev_i32_e32 v37, 31, v36
	v_lshlrev_b64 v[36:37], 13, v[36:37]
	v_lshl_add_u64 v[36:37], s[4:5], 0, v[36:37]
	v_lshl_add_u64 v[34:35], v[36:37], 0, v[66:67]
	s_mov_b64 s[6:7], -1
	s_and_b64 vcc, exec, s[40:41]
	s_waitcnt vmcnt(2)
	v_fma_f32 v38, v18, v58, v212
	v_or_b32_e32 v18, v52, v181
	v_add_u32_e32 v36, s38, v18
	v_mul_hi_i32 v37, v36, s0
	global_store_dword v[34:35], v38, off
	v_lshrrev_b32_e32 v38, 31, v37
	v_ashrrev_i32_e32 v37, 11, v37
	v_add_u32_e32 v61, v37, v38
	v_mad_i32_i24 v62, v61, s1, v36
	v_cmp_lt_i32_e64 s[48:49], s37, v62
	s_cbranch_vccnz .LBB0_1381
	s_and_saveexec_b64 s[6:7], s[48:49]
	s_xor_b64 s[6:7], exec, s[6:7]
	v_lshlrev_b32_e32 v36, 13, v61
	s_movk_i32 s10, 0xff00
	v_add3_u32 v36, v36, v62, s10
	s_or_saveexec_b64 s[6:7], s[6:7]
	v_mov_b64_e32 v[38:39], s[76:77]
	s_xor_b64 exec, exec, s[6:7]
	v_lshl_add_u32 v36, v61, 8, v62
	v_mov_b64_e32 v[38:39], s[12:13]
	s_or_b64 exec, exec, s[6:7]
	s_mov_b64 s[6:7], 0

; DI int crow(int i, int h) { return (i & 3) + 8 * (i >> 2) + 4 * h; }
; DI const float* xrow(CP p, const Ptrs& w, int l, int tok) {
;   int b = tok / TPB, i = tok - b * TPB;
;   if (l == 0) return i < CTXL ? p.in[2] + (size_t)(b * CTXL + i) * DM : p.in[0] + (size_t)(b * 8192 + i - CTXL) * DM;
;   return i < CTXL ? w.xc1 + (size_t)(b * CTXL + i) * DM : p.out + (size_t)(b * 8192 + i - CTXL) * DM;
; DI void phase_out(CP p, const Ptrs& w, int l, bf16_t* sA, bf16_t* sB) {
;     ...
;         int col = n0 + wn * 64 + ni * 32 + r;
;         float gt = gate[col];
; #pragma unroll
;         for (int i = 0; i < 16; ++i) {
;           int ii = ib + wm * 64 + mi * 32 + crow(i, h);
;           const float* src = xrow(p, w, l, b * TPB + ii);
;           float* dstp = isctx ? w.xc1 + (size_t)(b * CTXL + ii) * DM : p.out + (size_t)(b * 8192 + ii - CTXL) * DM;
;           dstp[col] = src[col] + gt * acc[mi][ni][i];
.LBB0_1387:
	v_ashrrev_i32_e32 v37, 31, v36
	v_lshlrev_b64 v[36:37], 13, v[36:37]
	v_lshl_add_u64 v[36:37], v[38:39], 0, v[36:37]
	v_lshl_add_u64 v[36:37], v[36:37], 0, v[66:67]
	v_add_u32_e32 v38, s39, v18
	v_ashrrev_i32_e32 v39, 31, v38
	v_lshlrev_b64 v[38:39], 13, v[38:39]
	v_lshl_add_u64 v[38:39], s[4:5], 0, v[38:39]
	v_or_b32_e32 v40, v52, v182
	s_mov_b64 s[6:7], -1
	s_and_b64 vcc, exec, s[40:41]
	s_waitcnt vmcnt(3)
	v_fma_f32 v36, v19, v58, v213
	v_lshl_add_u64 v[18:19], v[38:39], 0, v[66:67]
	global_store_dword v[18:19], v36, off
	v_add_u32_e32 v36, s38, v40
	v_mul_hi_i32 v37, v36, s0
	v_lshrrev_b32_e32 v38, 31, v37
	v_ashrrev_i32_e32 v37, 11, v37
	v_add_u32_e32 v63, v37, v38
	v_mad_i32_i24 v68, v63, s1, v36
	v_cmp_lt_i32_e64 s[50:51], s37, v68
	s_cbranch_vccnz .LBB0_1393
	s_and_saveexec_b64 s[6:7], s[50:51]
	s_xor_b64 s[6:7], exec, s[6:7]
	v_lshlrev_b32_e32 v36, 13, v63
	s_movk_i32 s10, 0xff00
	v_add3_u32 v36, v36, v68, s10
	s_or_saveexec_b64 s[6:7], s[6:7]
	v_mov_b64_e32 v[38:39], s[76:77]
	s_xor_b64 exec, exec, s[6:7]
	v_lshl_add_u32 v36, v63, 8, v68
	v_mov_b64_e32 v[38:39], s[12:13]
	s_or_b64 exec, exec, s[6:7]
	s_mov_b64 s[6:7], 0

; DI int crow(int i, int h) { return (i & 3) + 8 * (i >> 2) + 4 * h; }
; DI const float* xrow(CP p, const Ptrs& w, int l, int tok) {
;   int b = tok / TPB, i = tok - b * TPB;
;   if (l == 0) return i < CTXL ? p.in[2] + (size_t)(b * CTXL + i) * DM : p.in[0] + (size_t)(b * 8192 + i - CTXL) * DM;
;   return i < CTXL ? w.xc1 + (size_t)(b * CTXL + i) * DM : p.out + (size_t)(b * 8192 + i - CTXL) * DM;
; DI void phase_out(CP p, const Ptrs& w, int l, bf16_t* sA, bf16_t* sB) {
;     ...
;         int col = n0 + wn * 64 + ni * 32 + r;
;         float gt = gate[col];
; #pragma unroll
;         for (int i = 0; i < 16; ++i) {
;           int ii = ib + wm * 64 + mi * 32 + crow(i, h);
;           const float* src = xrow(p, w, l, b * TPB + ii);
;           float* dstp = isctx ? w.xc1 + (size_t)(b * CTXL + ii) * DM : p.out + (size_t)(b * 8192 + ii - CTXL) * DM;
;           dstp[col] = src[col] + gt * acc[mi][ni][i];
.LBB0_1399:
	v_ashrrev_i32_e32 v37, 31, v36
	v_lshlrev_b64 v[36:37], 13, v[36:37]
	v_lshl_add_u64 v[36:37], v[38:39], 0, v[36:37]
	v_lshl_add_u64 v[36:37], v[36:37], 0, v[66:67]
	v_add_u32_e32 v38, s39, v40
	v_ashrrev_i32_e32 v39, 31, v38
	v_lshlrev_b64 v[38:39], 13, v[38:39]
	v_lshl_add_u64 v[38:39], s[4:5], 0, v[38:39]
	v_lshl_add_u64 v[36:37], v[38:39], 0, v[66:67]
	s_mov_b64 s[6:7], -1
	s_and_b64 vcc, exec, s[40:41]
	s_waitcnt vmcnt(4)
	v_fma_f32 v40, v20, v58, v172
	v_or_b32_e32 v20, v52, v183
	v_add_u32_e32 v38, s38, v20
	v_mul_hi_i32 v39, v38, s0
	global_store_dword v[36:37], v40, off
	v_lshrrev_b32_e32 v40, 31, v39
	v_ashrrev_i32_e32 v39, 11, v39
	v_add_u32_e32 v69, v39, v40
	v_mad_i32_i24 v70, v69, s1, v38
	v_cmp_lt_i32_e64 s[52:53], s37, v70
	s_cbranch_vccnz .LBB0_1405
	s_and_saveexec_b64 s[6:7], s[52:53]
	s_xor_b64 s[6:7], exec, s[6:7]
	v_lshlrev_b32_e32 v38, 13, v69
	s_movk_i32 s10, 0xff00
	v_add3_u32 v38, v38, v70, s10
	s_or_saveexec_b64 s[6:7], s[6:7]
	v_mov_b64_e32 v[40:41], s[76:77]
	s_xor_b64 exec, exec, s[6:7]
	v_lshl_add_u32 v38, v69, 8, v70
	v_mov_b64_e32 v[40:41], s[12:13]
	s_or_b64 exec, exec, s[6:7]
	s_mov_b64 s[6:7], 0

; DI int crow(int i, int h) { return (i & 3) + 8 * (i >> 2) + 4 * h; }
; DI const float* xrow(CP p, const Ptrs& w, int l, int tok) {
;   int b = tok / TPB, i = tok - b * TPB;
;   if (l == 0) return i < CTXL ? p.in[2] + (size_t)(b * CTXL + i) * DM : p.in[0] + (size_t)(b * 8192 + i - CTXL) * DM;
;   return i < CTXL ? w.xc1 + (size_t)(b * CTXL + i) * DM : p.out + (size_t)(b * 8192 + i - CTXL) * DM;
; DI void phase_out(CP p, const Ptrs& w, int l, bf16_t* sA, bf16_t* sB) {
;     ...
;         int col = n0 + wn * 64 + ni * 32 + r;
;         float gt = gate[col];
; #pragma unroll
;         for (int i = 0; i < 16; ++i) {
;           int ii = ib + wm * 64 + mi * 32 + crow(i, h);
;           const float* src = xrow(p, w, l, b * TPB + ii);
;           float* dstp = isctx ? w.xc1 + (size_t)(b * CTXL + ii) * DM : p.out + (size_t)(b * 8192 + ii - CTXL) * DM;
;           dstp[col] = src[col] + gt * acc[mi][ni][i];
.LBB0_1411:
	v_ashrrev_i32_e32 v39, 31, v38
	v_lshlrev_b64 v[38:39], 13, v[38:39]
	v_lshl_add_u64 v[38:39], v[40:41], 0, v[38:39]
	v_lshl_add_u64 v[38:39], v[38:39], 0, v[66:67]
	v_add_u32_e32 v40, s39, v20
	v_ashrrev_i32_e32 v41, 31, v40
	v_lshlrev_b64 v[40:41], 13, v[40:41]
	v_lshl_add_u64 v[40:41], s[4:5], 0, v[40:41]
	v_or_b32_e32 v42, v52, v184
	s_mov_b64 s[6:7], -1
	s_and_b64 vcc, exec, s[40:41]
	s_waitcnt vmcnt(5)
	v_fma_f32 v38, v21, v58, v173
	v_lshl_add_u64 v[20:21], v[40:41], 0, v[66:67]
	global_store_dword v[20:21], v38, off
	v_add_u32_e32 v38, s38, v42
	v_mul_hi_i32 v39, v38, s0
	v_lshrrev_b32_e32 v40, 31, v39
	v_ashrrev_i32_e32 v39, 11, v39
	v_add_u32_e32 v71, v39, v40
	v_mad_i32_i24 v72, v71, s1, v38
	v_cmp_lt_i32_e64 s[54:55], s37, v72
	s_cbranch_vccnz .LBB0_1417
	s_and_saveexec_b64 s[6:7], s[54:55]
	s_xor_b64 s[6:7], exec, s[6:7]
	v_lshlrev_b32_e32 v38, 13, v71
	s_movk_i32 s10, 0xff00
	v_add3_u32 v38, v38, v72, s10
	s_or_saveexec_b64 s[6:7], s[6:7]
	v_mov_b64_e32 v[40:41], s[76:77]
	s_xor_b64 exec, exec, s[6:7]
	v_lshl_add_u32 v38, v71, 8, v72
	v_mov_b64_e32 v[40:41], s[12:13]
	s_or_b64 exec, exec, s[6:7]
	s_mov_b64 s[6:7], 0

; DI int crow(int i, int h) { return (i & 3) + 8 * (i >> 2) + 4 * h; }
; DI const float* xrow(CP p, const Ptrs& w, int l, int tok) {
;   int b = tok / TPB, i = tok - b * TPB;
;   if (l == 0) return i < CTXL ? p.in[2] + (size_t)(b * CTXL + i) * DM : p.in[0] + (size_t)(b * 8192 + i - CTXL) * DM;
;   return i < CTXL ? w.xc1 + (size_t)(b * CTXL + i) * DM : p.out + (size_t)(b * 8192 + i - CTXL) * DM;
; DI void phase_out(CP p, const Ptrs& w, int l, bf16_t* sA, bf16_t* sB) {
;     ...
;         int col = n0 + wn * 64 + ni * 32 + r;
;         float gt = gate[col];
; #pragma unroll
;         for (int i = 0; i < 16; ++i) {
;           int ii = ib + wm * 64 + mi * 32 + crow(i, h);
;           const float* src = xrow(p, w, l, b * TPB + ii);
;           float* dstp = isctx ? w.xc1 + (size_t)(b * CTXL + ii) * DM : p.out + (size_t)(b * 8192 + ii - CTXL) * DM;
;           dstp[col] = src[col] + gt * acc[mi][ni][i];
.LBB0_1423:
	v_ashrrev_i32_e32 v39, 31, v38
	v_lshlrev_b64 v[38:39], 13, v[38:39]
	v_lshl_add_u64 v[38:39], v[40:41], 0, v[38:39]
	v_lshl_add_u64 v[38:39], v[38:39], 0, v[66:67]
	v_add_u32_e32 v40, s39, v42
	v_ashrrev_i32_e32 v41, 31, v40
	v_lshlrev_b64 v[40:41], 13, v[40:41]
	v_lshl_add_u64 v[40:41], s[4:5], 0, v[40:41]
	v_lshl_add_u64 v[38:39], v[40:41], 0, v[66:67]
	s_mov_b64 s[6:7], -1
	s_and_b64 vcc, exec, s[40:41]
	s_waitcnt vmcnt(6)
	v_fma_f32 v42, v22, v58, v174
	v_or_b32_e32 v22, v52, v185
	v_add_u32_e32 v40, s38, v22
	v_mul_hi_i32 v41, v40, s0
	global_store_dword v[38:39], v42, off
	v_lshrrev_b32_e32 v42, 31, v41
	v_ashrrev_i32_e32 v41, 11, v41
	v_add_u32_e32 v73, v41, v42
	v_mad_i32_i24 v74, v73, s1, v40
	v_cmp_lt_i32_e64 s[56:57], s37, v74
	s_cbranch_vccnz .LBB0_1429
	s_and_saveexec_b64 s[6:7], s[56:57]
	s_xor_b64 s[6:7], exec, s[6:7]
	v_lshlrev_b32_e32 v40, 13, v73
	s_movk_i32 s10, 0xff00
	v_add3_u32 v40, v40, v74, s10
	s_or_saveexec_b64 s[6:7], s[6:7]
	v_mov_b64_e32 v[42:43], s[76:77]
	s_xor_b64 exec, exec, s[6:7]
	v_lshl_add_u32 v40, v73, 8, v74
	v_mov_b64_e32 v[42:43], s[12:13]
	s_or_b64 exec, exec, s[6:7]
	s_mov_b64 s[6:7], 0

; DI int crow(int i, int h) { return (i & 3) + 8 * (i >> 2) + 4 * h; }
; DI const float* xrow(CP p, const Ptrs& w, int l, int tok) {
;   int b = tok / TPB, i = tok - b * TPB;
;   if (l == 0) return i < CTXL ? p.in[2] + (size_t)(b * CTXL + i) * DM : p.in[0] + (size_t)(b * 8192 + i - CTXL) * DM;
;   return i < CTXL ? w.xc1 + (size_t)(b * CTXL + i) * DM : p.out + (size_t)(b * 8192 + i - CTXL) * DM;
; DI void phase_out(CP p, const Ptrs& w, int l, bf16_t* sA, bf16_t* sB) {
;     ...
;         int col = n0 + wn * 64 + ni * 32 + r;
;         float gt = gate[col];
; #pragma unroll
;         for (int i = 0; i < 16; ++i) {
;           int ii = ib + wm * 64 + mi * 32 + crow(i, h);
;           const float* src = xrow(p, w, l, b * TPB + ii);
;           float* dstp = isctx ? w.xc1 + (size_t)(b * CTXL + ii) * DM : p.out + (size_t)(b * 8192 + ii - CTXL) * DM;
;           dstp[col] = src[col] + gt * acc[mi][ni][i];
.LBB0_1435:
	v_ashrrev_i32_e32 v41, 31, v40
	v_lshlrev_b64 v[40:41], 13, v[40:41]
	v_lshl_add_u64 v[40:41], v[42:43], 0, v[40:41]
	v_lshl_add_u64 v[40:41], v[40:41], 0, v[66:67]
	v_add_u32_e32 v42, s39, v22
	v_ashrrev_i32_e32 v43, 31, v42
	v_lshlrev_b64 v[42:43], 13, v[42:43]
	v_lshl_add_u64 v[42:43], s[4:5], 0, v[42:43]
	v_or_b32_e32 v44, v52, v186
	s_mov_b64 s[6:7], -1
	s_and_b64 vcc, exec, s[40:41]
	s_waitcnt vmcnt(7)
	v_fma_f32 v40, v23, v58, v175
	v_lshl_add_u64 v[22:23], v[42:43], 0, v[66:67]
	global_store_dword v[22:23], v40, off
	v_add_u32_e32 v40, s38, v44
	v_mul_hi_i32 v41, v40, s0
	v_lshrrev_b32_e32 v42, 31, v41
	v_ashrrev_i32_e32 v41, 11, v41
	v_add_u32_e32 v75, v41, v42
	v_mad_i32_i24 v76, v75, s1, v40
	v_cmp_lt_i32_e64 s[58:59], s37, v76
	s_cbranch_vccnz .LBB0_1441
	s_and_saveexec_b64 s[6:7], s[58:59]
	s_xor_b64 s[6:7], exec, s[6:7]
	v_lshlrev_b32_e32 v40, 13, v75
	s_movk_i32 s10, 0xff00
	v_add3_u32 v40, v40, v76, s10
	s_or_saveexec_b64 s[6:7], s[6:7]
	v_mov_b64_e32 v[42:43], s[76:77]
	s_xor_b64 exec, exec, s[6:7]
	v_lshl_add_u32 v40, v75, 8, v76
	v_mov_b64_e32 v[42:43], s[12:13]
	s_or_b64 exec, exec, s[6:7]
	s_mov_b64 s[6:7], 0

; DI int crow(int i, int h) { return (i & 3) + 8 * (i >> 2) + 4 * h; }
; DI const float* xrow(CP p, const Ptrs& w, int l, int tok) {
;   int b = tok / TPB, i = tok - b * TPB;
;   if (l == 0) return i < CTXL ? p.in[2] + (size_t)(b * CTXL + i) * DM : p.in[0] + (size_t)(b * 8192 + i - CTXL) * DM;
;   return i < CTXL ? w.xc1 + (size_t)(b * CTXL + i) * DM : p.out + (size_t)(b * 8192 + i - CTXL) * DM;
; DI void phase_out(CP p, const Ptrs& w, int l, bf16_t* sA, bf16_t* sB) {
;     ...
;         int col = n0 + wn * 64 + ni * 32 + r;
;         float gt = gate[col];
; #pragma unroll
;         for (int i = 0; i < 16; ++i) {
;           int ii = ib + wm * 64 + mi * 32 + crow(i, h);
;           const float* src = xrow(p, w, l, b * TPB + ii);
;           float* dstp = isctx ? w.xc1 + (size_t)(b * CTXL + ii) * DM : p.out + (size_t)(b * 8192 + ii - CTXL) * DM;
;           dstp[col] = src[col] + gt * acc[mi][ni][i];
.LBB0_1447:
	v_ashrrev_i32_e32 v41, 31, v40
	v_lshlrev_b64 v[40:41], 13, v[40:41]
	v_lshl_add_u64 v[40:41], v[42:43], 0, v[40:41]
	v_lshl_add_u64 v[40:41], v[40:41], 0, v[66:67]
	v_add_u32_e32 v42, s39, v44
	v_ashrrev_i32_e32 v43, 31, v42
	v_lshlrev_b64 v[42:43], 13, v[42:43]
	v_lshl_add_u64 v[42:43], s[4:5], 0, v[42:43]
	v_lshl_add_u64 v[40:41], v[42:43], 0, v[66:67]
	s_mov_b64 s[6:7], -1
	s_and_b64 vcc, exec, s[40:41]
	s_waitcnt vmcnt(8)
	v_fma_f32 v44, v24, v58, v176
	v_or_b32_e32 v24, v52, v187
	v_add_u32_e32 v42, s38, v24
	v_mul_hi_i32 v43, v42, s0
	global_store_dword v[40:41], v44, off
	v_lshrrev_b32_e32 v44, 31, v43
	v_ashrrev_i32_e32 v43, 11, v43
	v_add_u32_e32 v77, v43, v44
	v_mad_i32_i24 v78, v77, s1, v42
	v_cmp_lt_i32_e64 s[60:61], s37, v78
	s_cbranch_vccnz .LBB0_1453
	s_and_saveexec_b64 s[6:7], s[60:61]
	s_xor_b64 s[6:7], exec, s[6:7]
	v_lshlrev_b32_e32 v42, 13, v77
	s_movk_i32 s10, 0xff00
	v_add3_u32 v42, v42, v78, s10
	s_or_saveexec_b64 s[6:7], s[6:7]
	v_mov_b64_e32 v[44:45], s[76:77]
	s_xor_b64 exec, exec, s[6:7]
	v_lshl_add_u32 v42, v77, 8, v78
	v_mov_b64_e32 v[44:45], s[12:13]
	s_or_b64 exec, exec, s[6:7]
	s_mov_b64 s[6:7], 0

; DI int crow(int i, int h) { return (i & 3) + 8 * (i >> 2) + 4 * h; }
; DI const float* xrow(CP p, const Ptrs& w, int l, int tok) {
;   int b = tok / TPB, i = tok - b * TPB;
;   if (l == 0) return i < CTXL ? p.in[2] + (size_t)(b * CTXL + i) * DM : p.in[0] + (size_t)(b * 8192 + i - CTXL) * DM;
;   return i < CTXL ? w.xc1 + (size_t)(b * CTXL + i) * DM : p.out + (size_t)(b * 8192 + i - CTXL) * DM;
; DI void phase_out(CP p, const Ptrs& w, int l, bf16_t* sA, bf16_t* sB) {
;     ...
;         int col = n0 + wn * 64 + ni * 32 + r;
;         float gt = gate[col];
; #pragma unroll
;         for (int i = 0; i < 16; ++i) {
;           int ii = ib + wm * 64 + mi * 32 + crow(i, h);
;           const float* src = xrow(p, w, l, b * TPB + ii);
;           float* dstp = isctx ? w.xc1 + (size_t)(b * CTXL + ii) * DM : p.out + (size_t)(b * 8192 + ii - CTXL) * DM;
;           dstp[col] = src[col] + gt * acc[mi][ni][i];
.LBB0_1459:
	v_ashrrev_i32_e32 v43, 31, v42
	v_lshlrev_b64 v[42:43], 13, v[42:43]
	v_lshl_add_u64 v[42:43], v[44:45], 0, v[42:43]
	v_lshl_add_u64 v[42:43], v[42:43], 0, v[66:67]
	v_add_u32_e32 v44, s39, v24
	v_ashrrev_i32_e32 v45, 31, v44
	v_lshlrev_b64 v[44:45], 13, v[44:45]
	v_lshl_add_u64 v[44:45], s[4:5], 0, v[44:45]
	v_or_b32_e32 v46, v52, v188
	s_mov_b64 s[6:7], -1
	s_and_b64 vcc, exec, s[40:41]
	s_waitcnt vmcnt(9)
	v_fma_f32 v42, v25, v58, v177
	v_lshl_add_u64 v[24:25], v[44:45], 0, v[66:67]
	global_store_dword v[24:25], v42, off
	v_add_u32_e32 v42, s38, v46
	v_mul_hi_i32 v43, v42, s0
	v_lshrrev_b32_e32 v44, 31, v43
	v_ashrrev_i32_e32 v43, 11, v43
	v_add_u32_e32 v79, v43, v44
	v_mad_i32_i24 v80, v79, s1, v42
	v_cmp_lt_i32_e64 s[62:63], s37, v80
	s_cbranch_vccnz .LBB0_1465
	s_and_saveexec_b64 s[6:7], s[62:63]
	s_xor_b64 s[6:7], exec, s[6:7]
	v_lshlrev_b32_e32 v42, 13, v79
	s_movk_i32 s10, 0xff00
	v_add3_u32 v42, v42, v80, s10
	s_or_saveexec_b64 s[6:7], s[6:7]
	v_mov_b64_e32 v[44:45], s[76:77]
	s_xor_b64 exec, exec, s[6:7]
	v_lshl_add_u32 v42, v79, 8, v80
	v_mov_b64_e32 v[44:45], s[12:13]
	s_or_b64 exec, exec, s[6:7]
	s_mov_b64 s[6:7], 0

; DI int crow(int i, int h) { return (i & 3) + 8 * (i >> 2) + 4 * h; }
; DI const float* xrow(CP p, const Ptrs& w, int l, int tok) {
;   int b = tok / TPB, i = tok - b * TPB;
;   if (l == 0) return i < CTXL ? p.in[2] + (size_t)(b * CTXL + i) * DM : p.in[0] + (size_t)(b * 8192 + i - CTXL) * DM;
;   return i < CTXL ? w.xc1 + (size_t)(b * CTXL + i) * DM : p.out + (size_t)(b * 8192 + i - CTXL) * DM;
; DI void phase_out(CP p, const Ptrs& w, int l, bf16_t* sA, bf16_t* sB) {
;     ...
;         int col = n0 + wn * 64 + ni * 32 + r;
;         float gt = gate[col];
; #pragma unroll
;         for (int i = 0; i < 16; ++i) {
;           int ii = ib + wm * 64 + mi * 32 + crow(i, h);
;           const float* src = xrow(p, w, l, b * TPB + ii);
;           float* dstp = isctx ? w.xc1 + (size_t)(b * CTXL + ii) * DM : p.out + (size_t)(b * 8192 + ii - CTXL) * DM;
;           dstp[col] = src[col] + gt * acc[mi][ni][i];
.LBB0_1471:
	v_ashrrev_i32_e32 v43, 31, v42
	v_lshlrev_b64 v[42:43], 13, v[42:43]
	v_lshl_add_u64 v[42:43], v[44:45], 0, v[42:43]
	v_lshl_add_u64 v[42:43], v[42:43], 0, v[66:67]
	v_add_u32_e32 v44, s39, v46
	v_ashrrev_i32_e32 v45, 31, v44
	v_lshlrev_b64 v[44:45], 13, v[44:45]
	v_lshl_add_u64 v[44:45], s[4:5], 0, v[44:45]
	v_lshl_add_u64 v[42:43], v[44:45], 0, v[66:67]
	s_mov_b64 s[6:7], -1
	s_and_b64 vcc, exec, s[40:41]
	s_waitcnt vmcnt(10)
	v_fma_f32 v46, v26, v58, v178
	v_or_b32_e32 v26, v52, v189
	v_add_u32_e32 v44, s38, v26
	v_mul_hi_i32 v45, v44, s0
	global_store_dword v[42:43], v46, off
	v_lshrrev_b32_e32 v46, 31, v45
	v_ashrrev_i32_e32 v45, 11, v45
	v_add_u32_e32 v81, v45, v46
	v_mad_i32_i24 v82, v81, s1, v44
	v_cmp_lt_i32_e64 s[64:65], s37, v82
	s_cbranch_vccnz .LBB0_1477
	s_and_saveexec_b64 s[6:7], s[64:65]
	s_xor_b64 s[6:7], exec, s[6:7]
	v_lshlrev_b32_e32 v44, 13, v81
	s_movk_i32 s10, 0xff00
	v_add3_u32 v44, v44, v82, s10
	s_or_saveexec_b64 s[6:7], s[6:7]
	v_mov_b64_e32 v[46:47], s[76:77]
	s_xor_b64 exec, exec, s[6:7]
	v_lshl_add_u32 v44, v81, 8, v82
	v_mov_b64_e32 v[46:47], s[12:13]
	s_or_b64 exec, exec, s[6:7]
	s_mov_b64 s[6:7], 0

; DI int crow(int i, int h) { return (i & 3) + 8 * (i >> 2) + 4 * h; }
; DI const float* xrow(CP p, const Ptrs& w, int l, int tok) {
;   int b = tok / TPB, i = tok - b * TPB;
;   if (l == 0) return i < CTXL ? p.in[2] + (size_t)(b * CTXL + i) * DM : p.in[0] + (size_t)(b * 8192 + i - CTXL) * DM;
;   return i < CTXL ? w.xc1 + (size_t)(b * CTXL + i) * DM : p.out + (size_t)(b * 8192 + i - CTXL) * DM;
; DI void phase_out(CP p, const Ptrs& w, int l, bf16_t* sA, bf16_t* sB) {
;     ...
;         int col = n0 + wn * 64 + ni * 32 + r;
;         float gt = gate[col];
; #pragma unroll
;         for (int i = 0; i < 16; ++i) {
;           int ii = ib + wm * 64 + mi * 32 + crow(i, h);
;           const float* src = xrow(p, w, l, b * TPB + ii);
;           float* dstp = isctx ? w.xc1 + (size_t)(b * CTXL + ii) * DM : p.out + (size_t)(b * 8192 + ii - CTXL) * DM;
;           dstp[col] = src[col] + gt * acc[mi][ni][i];
.LBB0_1483:
	v_ashrrev_i32_e32 v45, 31, v44
	v_lshlrev_b64 v[44:45], 13, v[44:45]
	v_lshl_add_u64 v[44:45], v[46:47], 0, v[44:45]
	v_lshl_add_u64 v[44:45], v[44:45], 0, v[66:67]
	v_add_u32_e32 v46, s39, v26
	v_ashrrev_i32_e32 v47, 31, v46
	v_lshlrev_b64 v[46:47], 13, v[46:47]
	v_lshl_add_u64 v[46:47], s[4:5], 0, v[46:47]
	v_or_b32_e32 v50, v52, v190
	s_mov_b64 s[6:7], -1
	s_and_b64 vcc, exec, s[40:41]
	s_waitcnt vmcnt(11)
	v_fma_f32 v44, v27, v58, v179
	v_lshl_add_u64 v[26:27], v[46:47], 0, v[66:67]
	global_store_dword v[26:27], v44, off
	v_add_u32_e32 v44, s38, v50
	v_mul_hi_i32 v45, v44, s0
	v_lshrrev_b32_e32 v46, 31, v45
	v_ashrrev_i32_e32 v45, 11, v45
	v_add_u32_e32 v83, v45, v46
	v_mad_i32_i24 v84, v83, s1, v44
	v_cmp_lt_i32_e64 s[66:67], s37, v84
	s_cbranch_vccnz .LBB0_1489
	s_and_saveexec_b64 s[6:7], s[66:67]
	s_xor_b64 s[6:7], exec, s[6:7]
	v_lshlrev_b32_e32 v44, 13, v83
	s_movk_i32 s10, 0xff00
	v_add3_u32 v44, v44, v84, s10
	s_or_saveexec_b64 s[6:7], s[6:7]
	v_mov_b64_e32 v[46:47], s[76:77]
	s_xor_b64 exec, exec, s[6:7]
	v_lshl_add_u32 v44, v83, 8, v84
	v_mov_b64_e32 v[46:47], s[12:13]
	s_or_b64 exec, exec, s[6:7]
	s_mov_b64 s[6:7], 0

; DI int crow(int i, int h) { return (i & 3) + 8 * (i >> 2) + 4 * h; }
; DI const float* xrow(CP p, const Ptrs& w, int l, int tok) {
;   int b = tok / TPB, i = tok - b * TPB;
;   if (l == 0) return i < CTXL ? p.in[2] + (size_t)(b * CTXL + i) * DM : p.in[0] + (size_t)(b * 8192 + i - CTXL) * DM;
;   return i < CTXL ? w.xc1 + (size_t)(b * CTXL + i) * DM : p.out + (size_t)(b * 8192 + i - CTXL) * DM;
; DI void phase_out(CP p, const Ptrs& w, int l, bf16_t* sA, bf16_t* sB) {
;     ...
;         int col = n0 + wn * 64 + ni * 32 + r;
;         float gt = gate[col];
; #pragma unroll
;         for (int i = 0; i < 16; ++i) {
;           int ii = ib + wm * 64 + mi * 32 + crow(i, h);
;           const float* src = xrow(p, w, l, b * TPB + ii);
;           float* dstp = isctx ? w.xc1 + (size_t)(b * CTXL + ii) * DM : p.out + (size_t)(b * 8192 + ii - CTXL) * DM;
;           dstp[col] = src[col] + gt * acc[mi][ni][i];
.LBB0_1495:
	v_ashrrev_i32_e32 v45, 31, v44
	v_lshlrev_b64 v[44:45], 13, v[44:45]
	v_lshl_add_u64 v[44:45], v[46:47], 0, v[44:45]
	v_lshl_add_u64 v[44:45], v[44:45], 0, v[66:67]
	v_add_u32_e32 v46, s39, v50
	v_ashrrev_i32_e32 v47, 31, v46
	v_lshlrev_b64 v[46:47], 13, v[46:47]
	v_lshl_add_u64 v[46:47], s[4:5], 0, v[46:47]
	v_lshl_add_u64 v[44:45], v[46:47], 0, v[66:67]
	s_mov_b64 s[6:7], -1
	s_and_b64 vcc, exec, s[40:41]
	s_waitcnt vmcnt(12)
	v_fma_f32 v50, v28, v58, v132
	v_or_b32_e32 v28, v52, v191
	v_add_u32_e32 v46, s38, v28
	v_mul_hi_i32 v47, v46, s0
	global_store_dword v[44:45], v50, off
	v_lshrrev_b32_e32 v50, 31, v47
	v_ashrrev_i32_e32 v47, 11, v47
	v_add_u32_e32 v85, v47, v50
	v_mad_i32_i24 v86, v85, s1, v46
	v_cmp_lt_i32_e64 s[68:69], s37, v86
	s_cbranch_vccnz .LBB0_1501
	s_and_saveexec_b64 s[6:7], s[68:69]
	s_xor_b64 s[6:7], exec, s[6:7]
	v_lshlrev_b32_e32 v46, 13, v85
	s_movk_i32 s10, 0xff00
	v_add3_u32 v46, v46, v86, s10
	s_or_saveexec_b64 s[6:7], s[6:7]
	v_mov_b64_e32 v[50:51], s[76:77]
	s_xor_b64 exec, exec, s[6:7]
	v_lshl_add_u32 v46, v85, 8, v86
	v_mov_b64_e32 v[50:51], s[12:13]
	s_or_b64 exec, exec, s[6:7]
	s_mov_b64 s[6:7], 0

; DI int crow(int i, int h) { return (i & 3) + 8 * (i >> 2) + 4 * h; }
; DI const float* xrow(CP p, const Ptrs& w, int l, int tok) {
;   int b = tok / TPB, i = tok - b * TPB;
;   if (l == 0) return i < CTXL ? p.in[2] + (size_t)(b * CTXL + i) * DM : p.in[0] + (size_t)(b * 8192 + i - CTXL) * DM;
;   return i < CTXL ? w.xc1 + (size_t)(b * CTXL + i) * DM : p.out + (size_t)(b * 8192 + i - CTXL) * DM;
; DI void phase_out(CP p, const Ptrs& w, int l, bf16_t* sA, bf16_t* sB) {
;     ...
;         int col = n0 + wn * 64 + ni * 32 + r;
;         float gt = gate[col];
; #pragma unroll
;         for (int i = 0; i < 16; ++i) {
;           int ii = ib + wm * 64 + mi * 32 + crow(i, h);
;           const float* src = xrow(p, w, l, b * TPB + ii);
;           float* dstp = isctx ? w.xc1 + (size_t)(b * CTXL + ii) * DM : p.out + (size_t)(b * 8192 + ii - CTXL) * DM;
;           dstp[col] = src[col] + gt * acc[mi][ni][i];
.LBB0_1507:
	v_ashrrev_i32_e32 v47, 31, v46
	v_lshlrev_b64 v[46:47], 13, v[46:47]
	v_lshl_add_u64 v[46:47], v[50:51], 0, v[46:47]
	v_lshl_add_u64 v[46:47], v[46:47], 0, v[66:67]
	v_add_u32_e32 v50, s39, v28
	v_ashrrev_i32_e32 v51, 31, v50
	v_lshlrev_b64 v[50:51], 13, v[50:51]
	v_lshl_add_u64 v[50:51], s[4:5], 0, v[50:51]
	v_or_b32_e32 v53, v52, v192
	s_mov_b64 s[6:7], -1
	s_and_b64 vcc, exec, s[40:41]
	s_waitcnt vmcnt(13)
	v_fma_f32 v46, v29, v58, v133
	v_lshl_add_u64 v[28:29], v[50:51], 0, v[66:67]
	global_store_dword v[28:29], v46, off
	v_add_u32_e32 v46, s38, v53
	v_mul_hi_i32 v47, v46, s0
	v_lshrrev_b32_e32 v50, 31, v47
	v_ashrrev_i32_e32 v47, 11, v47
	v_add_u32_e32 v87, v47, v50
	v_mad_i32_i24 v88, v87, s1, v46
	v_cmp_lt_i32_e64 s[70:71], s37, v88
	s_cbranch_vccnz .LBB0_1513
	s_and_saveexec_b64 s[6:7], s[70:71]
	s_xor_b64 s[6:7], exec, s[6:7]
	v_lshlrev_b32_e32 v46, 13, v87
	s_movk_i32 s10, 0xff00
	v_add3_u32 v46, v46, v88, s10
	s_or_saveexec_b64 s[6:7], s[6:7]
	v_mov_b64_e32 v[50:51], s[76:77]
	s_xor_b64 exec, exec, s[6:7]
	v_lshl_add_u32 v46, v87, 8, v88
	v_mov_b64_e32 v[50:51], s[12:13]
	s_or_b64 exec, exec, s[6:7]
	s_mov_b64 s[6:7], 0

; DI int crow(int i, int h) { return (i & 3) + 8 * (i >> 2) + 4 * h; }
; DI const float* xrow(CP p, const Ptrs& w, int l, int tok) {
;   int b = tok / TPB, i = tok - b * TPB;
;   if (l == 0) return i < CTXL ? p.in[2] + (size_t)(b * CTXL + i) * DM : p.in[0] + (size_t)(b * 8192 + i - CTXL) * DM;
;   return i < CTXL ? w.xc1 + (size_t)(b * CTXL + i) * DM : p.out + (size_t)(b * 8192 + i - CTXL) * DM;
; DI void phase_out(CP p, const Ptrs& w, int l, bf16_t* sA, bf16_t* sB) {
;     ...
;         int col = n0 + wn * 64 + ni * 32 + r;
;         float gt = gate[col];
; #pragma unroll
;         for (int i = 0; i < 16; ++i) {
;           int ii = ib + wm * 64 + mi * 32 + crow(i, h);
;           const float* src = xrow(p, w, l, b * TPB + ii);
;           float* dstp = isctx ? w.xc1 + (size_t)(b * CTXL + ii) * DM : p.out + (size_t)(b * 8192 + ii - CTXL) * DM;
;           dstp[col] = src[col] + gt * acc[mi][ni][i];
.LBB0_1519:
	v_ashrrev_i32_e32 v47, 31, v46
	v_lshlrev_b64 v[46:47], 13, v[46:47]
	v_lshl_add_u64 v[46:47], v[50:51], 0, v[46:47]
	v_lshl_add_u64 v[46:47], v[46:47], 0, v[66:67]
	v_add_u32_e32 v50, s39, v53
	v_ashrrev_i32_e32 v51, 31, v50
	v_lshlrev_b64 v[50:51], 13, v[50:51]
	v_lshl_add_u64 v[50:51], s[4:5], 0, v[50:51]
	v_lshl_add_u64 v[46:47], v[50:51], 0, v[66:67]
	s_mov_b64 s[6:7], -1
	s_and_b64 vcc, exec, s[40:41]
	s_waitcnt vmcnt(14)
	v_fma_f32 v53, v30, v58, v134
	v_or_b32_e32 v30, v52, v193
	v_add_u32_e32 v50, s38, v30
	v_mul_hi_i32 v51, v50, s0
	v_lshrrev_b32_e32 v52, 31, v51
	v_ashrrev_i32_e32 v51, 11, v51
	v_add_u32_e32 v89, v51, v52
	v_mad_i32_i24 v90, v89, s1, v50
	v_cmp_lt_i32_e64 s[72:73], s37, v90
	global_store_dword v[46:47], v53, off
	s_cbranch_vccnz .LBB0_1525
	s_and_saveexec_b64 s[6:7], s[72:73]
	s_xor_b64 s[6:7], exec, s[6:7]
	v_lshlrev_b32_e32 v50, 13, v89
	s_movk_i32 s10, 0xff00
	v_add3_u32 v50, v50, v90, s10
	s_or_saveexec_b64 s[6:7], s[6:7]
	v_mov_b64_e32 v[52:53], s[76:77]
	s_xor_b64 exec, exec, s[6:7]
	v_lshl_add_u32 v50, v89, 8, v90
	v_mov_b64_e32 v[52:53], s[12:13]
	s_or_b64 exec, exec, s[6:7]
	s_mov_b64 s[6:7], 0

; DI int crow(int i, int h) { return (i & 3) + 8 * (i >> 2) + 4 * h; }
; DI void phase_out(CP p, const Ptrs& w, int l, bf16_t* sA, bf16_t* sB) {
;     ...
;         int col = n0 + wn * 64 + ni * 32 + r;
;         float gt = gate[col];
; #pragma unroll
;         for (int i = 0; i < 16; ++i) {
;           int ii = ib + wm * 64 + mi * 32 + crow(i, h);
;           const float* src = xrow(p, w, l, b * TPB + ii);
;           float* dstp = isctx ? w.xc1 + (size_t)(b * CTXL + ii) * DM : p.out + (size_t)(b * 8192 + ii - CTXL) * DM;
;           dstp[col] = src[col] + gt * acc[mi][ni][i];
.LBB0_1531:
	v_ashrrev_i32_e32 v51, 31, v50
	v_lshlrev_b64 v[50:51], 13, v[50:51]
	v_lshl_add_u64 v[50:51], v[52:53], 0, v[50:51]
	v_lshl_add_u64 v[50:51], v[50:51], 0, v[66:67]
	v_add_u32_e32 v50, s39, v30
	v_ashrrev_i32_e32 v51, 31, v50
	v_lshlrev_b64 v[50:51], 13, v[50:51]
	v_lshl_add_u64 v[50:51], s[4:5], 0, v[50:51]
	s_and_b64 vcc, exec, s[40:41]
	s_mov_b64 s[4:5], -1
	s_waitcnt vmcnt(15)
	v_fma_f32 v52, v31, v58, v135
	v_lshl_add_u64 v[30:31], v[50:51], 0, v[66:67]
	global_store_dword v[30:31], v52, off
	global_load_dword v52, v[48:49], off
	s_cbranch_vccnz .LBB0_1537
	s_and_saveexec_b64 s[4:5], s[42:43]
	s_xor_b64 s[4:5], exec, s[4:5]
	v_lshlrev_b32_e32 v48, 13, v54
	s_movk_i32 s6, 0xff00
	v_add3_u32 v48, v48, v55, s6
	s_or_saveexec_b64 s[4:5], s[4:5]
	v_mov_b64_e32 v[50:51], s[76:77]
	s_xor_b64 exec, exec, s[4:5]
	v_lshl_add_u32 v48, v54, 8, v55
	v_mov_b64_e32 v[50:51], s[12:13]
	s_or_b64 exec, exec, s[4:5]
	s_mov_b64 s[4:5], 0
